# v26 + SwiGLU epilogue operands prefetched into LDS by DMA at unit start (no global-load wait in the epilogue) + residual epilogue: second-half row loads issued with the first half
# baseline (speedup 1.0000x reference)
; #define PG8_STAGE(bufoff, gbase, voff) do { _Pragma("unroll") for (int _i = 0; _i < 2; ++_i) \
;         __builtin_amdgcn_global_load_lds((const unsigned*)((const char*)(gbase) + (voff)[_i]), (PG8_LAS unsigned*)(lds + (bufoff) + ldsw + _i * 8192), 16, 0, 0); } while (0)
; #define PG8_LDA(dst, b, h) do { _Pragma("unroll") for (int m = 0; m < 4; ++m) _Pragma("unroll") for (int k = 0; k < 2; ++k) dst[m][k] = *(const PG8_LAS bf16x8*)(lds + PG8_SA(b, h) + aoff + m * 2048 + k * 1024); } while (0)
; #define PG8_LDB(dst, b, h) do { _Pragma("unroll") for (int n = 0; n < 2; ++n) _Pragma("unroll") for (int k = 0; k < 2; ++k) dst[n][k] = *(const PG8_LAS bf16x8*)(lds + PG8_SB(b, h) + boff + n * 2048 + k * 1024); } while (0)
; #define PG8_MMA(ai, bj, At, Bt) do { __builtin_amdgcn_s_setprio(1); _Pragma("unroll") for (int m = 0; m < 4; ++m) _Pragma("unroll") for (int n = 0; n < 2; ++n) _Pragma("unroll") for (int k = 0; k < 2; ++k) \
;         acc[ai][bj][m][n] = __builtin_amdgcn_mfma_f32_16x16x32_bf16(Bt[n][k], At[m][k], acc[ai][bj][m][n], 0, 0, 0); __builtin_amdgcn_s_setprio(0); } while (0)
; #define PG8_WAIT_V(n) asm volatile("s_waitcnt vmcnt(" #n ")" ::: "memory")
; #define PG8_WAIT_L(n) asm volatile("s_waitcnt lgkmcnt(" #n ")" ::: "memory")
; #define PG8_BAR __builtin_amdgcn_s_barrier()
; #define PG8_SCHED __builtin_amdgcn_sched_barrier(0)
; template <class Epi, class Sched, bool ALIGN_EPI = false, bool SP2 = false>
; __device__ __forceinline__ void gemm_phase(PG8_LAS unsigned char* lds, const int tid, const Gemm g, const Sched& S, const Epi& E) {
;     ...
;     const int aoff = lds_byte(wr * 64 + fr, fq * 8), boff = lds_byte(wc * 32 + fr, fq * 8);
;     ...
;             PG8_LDB(B0, 0, 0); PG8_LDB(B1, 0, 1); PG8_SCHED; PG8_LDA(At, 0, 0); PG8_STAGE(PG8_SA(1, 1), a1 + hstep, voffA);
;             PG8_WAIT_V(8); PG8_WAIT_L(0); PG8_BAR; PG8_MMA(0, 0, At, B0); PG8_MMA(0, 1, At, B1); PG8_BAR; PG8_SCHED;
;             PG8_LDA(At, 0, 1); PG8_STAGE(PG8_SB(0, 0), b2, voffB); PG8_STAGE(PG8_SB(0, 1), b2 + hstep, voffB); PG8_STAGE(PG8_SA(0, 0), a2, voffA);
;             PG8_WAIT_V(8); PG8_WAIT_L(0); PG8_BAR; PG8_MMA(1, 0, At, B0); PG8_MMA(1, 1, At, B1); PG8_BAR; PG8_SCHED;
.LBB0_310:
	s_add_u32 s38, s26, 0x80
	s_addc_u32 s39, s27, 0
	s_add_u32 s26, s24, 0x100
	s_addc_u32 s27, s25, 0
	s_mov_b32 s14, 0
	s_waitcnt lgkmcnt(0)
	v_xor_b32_e32 v246, 64, v232
	v_add_u32_e32 v247, 0x10000, v185
	v_xor_b32_e32 v248, 64, v185
	v_add_u32_e32 v248, 0x10000, v248
	s_add_i32 s51, s14, 2
	s_add_u32 s10, s38, 0x80
	s_addc_u32 s24, s39, 0
	s_cmp_eq_u32 s47, s14
	s_cselect_b32 s25, s29, s24
	s_cselect_b32 s24, s28, s10
	s_cselect_b32 s53, s43, s27
	s_cselect_b32 s52, s42, s26
	s_add_u32 s92, s38, s12
	s_addc_u32 s93, s39, 0
	ds_read_b128 v[72:75], v247
	ds_read_b128 v[76:79], v248
	ds_read_b128 v[136:139], v247 offset:2048
	ds_read_b128 v[140:143], v248 offset:2048
	ds_read_b128 v[144:147], v247 offset:16384
	ds_read_b128 v[148:151], v248 offset:16384
	ds_read_b128 v[152:155], v247 offset:18432
	ds_read_b128 v[156:159], v248 offset:18432
	s_add_i32 m0, s20, 0xc000
	ds_read_b128 v[160:163], v232
	ds_read_b128 v[164:167], v246
	ds_read_b128 v[196:199], v232 offset:2048
	ds_read_b128 v[200:203], v246 offset:2048
	ds_read_b128 v[204:207], v232 offset:4096
	ds_read_b128 v[208:211], v246 offset:4096
	ds_read_b128 v[212:215], v232 offset:6144
	ds_read_b128 v[216:219], v246 offset:6144
	global_load_lds_dwordx4 v190, s[92:93]
	s_add_i32 m0, s20, 0xe000
	s_nop 0
	global_load_lds_dwordx4 v188, s[92:93]
	s_waitcnt vmcnt(8)
	s_waitcnt lgkmcnt(0)
	s_barrier
	s_setprio 1
	s_waitcnt lgkmcnt(0)
	v_mfma_f32_16x16x32_bf16 v[132:135], v[72:75], v[160:163], 0
	v_mfma_f32_16x16x32_bf16 v[128:131], v[136:139], v[160:163], 0
	v_mfma_f32_16x16x32_bf16 v[116:119], v[72:75], v[196:199], 0
	v_mfma_f32_16x16x32_bf16 v[112:115], v[136:139], v[196:199], 0
	v_mfma_f32_16x16x32_bf16 v[100:103], v[72:75], v[204:207], 0
	v_mfma_f32_16x16x32_bf16 v[96:99], v[136:139], v[204:207], 0
	v_mfma_f32_16x16x32_bf16 v[84:87], v[72:75], v[212:215], 0
	v_mfma_f32_16x16x32_bf16 v[80:83], v[136:139], v[212:215], 0
	v_mfma_f32_16x16x32_bf16 v[132:135], v[76:79], v[164:167], v[132:135]
	v_mfma_f32_16x16x32_bf16 v[128:131], v[140:143], v[164:167], v[128:131]
	v_mfma_f32_16x16x32_bf16 v[116:119], v[76:79], v[200:203], v[116:119]
	v_mfma_f32_16x16x32_bf16 v[112:115], v[140:143], v[200:203], v[112:115]
	v_mfma_f32_16x16x32_bf16 v[100:103], v[76:79], v[208:211], v[100:103]
	v_mfma_f32_16x16x32_bf16 v[96:99], v[140:143], v[208:211], v[96:99]
	v_mfma_f32_16x16x32_bf16 v[84:87], v[76:79], v[216:219], v[84:87]
	v_mfma_f32_16x16x32_bf16 v[80:83], v[140:143], v[216:219], v[80:83]
	s_setprio 0
	s_setprio 1
	v_mfma_f32_16x16x32_bf16 v[124:127], v[144:147], v[160:163], 0
	v_mfma_f32_16x16x32_bf16 v[120:123], v[152:155], v[160:163], 0
	v_mfma_f32_16x16x32_bf16 v[108:111], v[144:147], v[196:199], 0
	v_mfma_f32_16x16x32_bf16 v[104:107], v[152:155], v[196:199], 0
	v_mfma_f32_16x16x32_bf16 v[92:95], v[144:147], v[204:207], 0
	v_mfma_f32_16x16x32_bf16 v[88:91], v[152:155], v[204:207], 0
	v_mfma_f32_16x16x32_bf16 v[68:71], v[144:147], v[212:215], 0
	v_mfma_f32_16x16x32_bf16 v[64:67], v[152:155], v[212:215], 0
	v_mfma_f32_16x16x32_bf16 v[124:127], v[148:151], v[164:167], v[124:127]
	v_mfma_f32_16x16x32_bf16 v[120:123], v[156:159], v[164:167], v[120:123]
	v_mfma_f32_16x16x32_bf16 v[108:111], v[148:151], v[200:203], v[108:111]
	v_mfma_f32_16x16x32_bf16 v[104:107], v[156:159], v[200:203], v[104:107]
	v_mfma_f32_16x16x32_bf16 v[92:95], v[148:151], v[208:211], v[92:95]
	v_mfma_f32_16x16x32_bf16 v[88:91], v[156:159], v[208:211], v[88:91]
	v_mfma_f32_16x16x32_bf16 v[68:71], v[148:151], v[216:219], v[68:71]
	v_mfma_f32_16x16x32_bf16 v[64:67], v[156:159], v[216:219], v[64:67]
	s_setprio 0
	s_barrier
	s_add_i32 m0, s15, 0x10000
	ds_read_b128 v[160:163], v232 offset:16384
	ds_read_b128 v[164:167], v246 offset:16384
	ds_read_b128 v[196:199], v232 offset:18432
	ds_read_b128 v[200:203], v246 offset:18432
	ds_read_b128 v[204:207], v232 offset:20480
	ds_read_b128 v[208:211], v246 offset:20480
	ds_read_b128 v[212:215], v232 offset:22528
	ds_read_b128 v[216:219], v246 offset:22528
	global_load_lds_dwordx4 v168, s[52:53]
	s_add_i32 m0, s15, 0x12000
	s_add_u32 s94, s52, 0x80
	s_addc_u32 s95, s53, 0
	global_load_lds_dwordx4 v186, s[52:53]
	s_add_u32 s52, s52, s12
	s_addc_u32 s53, s53, 0
	s_add_i32 m0, s15, 0x14000
	s_add_u32 s98, s24, 0x80
	s_addc_u32 s99, s25, 0
	global_load_lds_dwordx4 v168, s[52:53]
	s_add_i32 m0, s15, 0x16000
	s_nop 0
	global_load_lds_dwordx4 v186, s[52:53]
	s_mov_b32 m0, s20
	s_nop 0
	global_load_lds_dwordx4 v190, s[24:25]
	s_mov_b32 m0, s21
	s_nop 0
	global_load_lds_dwordx4 v188, s[24:25]
	s_waitcnt vmcnt(8)
	s_waitcnt lgkmcnt(0)
	s_barrier
; #define PG8_STAGE(bufoff, gbase, voff) do { _Pragma("unroll") for (int _i = 0; _i < 2; ++_i) \
;         __builtin_amdgcn_global_load_lds((const unsigned*)((const char*)(gbase) + (voff)[_i]), (PG8_LAS unsigned*)(lds + (bufoff) + ldsw + _i * 8192), 16, 0, 0); } while (0)
; #define PG8_LDA(dst, b, h) do { _Pragma("unroll") for (int m = 0; m < 4; ++m) _Pragma("unroll") for (int k = 0; k < 2; ++k) dst[m][k] = *(const PG8_LAS bf16x8*)(lds + PG8_SA(b, h) + aoff + m * 2048 + k * 1024); } while (0)
; #define PG8_LDB(dst, b, h) do { _Pragma("unroll") for (int n = 0; n < 2; ++n) _Pragma("unroll") for (int k = 0; k < 2; ++k) dst[n][k] = *(const PG8_LAS bf16x8*)(lds + PG8_SB(b, h) + boff + n * 2048 + k * 1024); } while (0)
; #define PG8_MMA(ai, bj, At, Bt) do { __builtin_amdgcn_s_setprio(1); _Pragma("unroll") for (int m = 0; m < 4; ++m) _Pragma("unroll") for (int n = 0; n < 2; ++n) _Pragma("unroll") for (int k = 0; k < 2; ++k) \
;         acc[ai][bj][m][n] = __builtin_amdgcn_mfma_f32_16x16x32_bf16(Bt[n][k], At[m][k], acc[ai][bj][m][n], 0, 0, 0); __builtin_amdgcn_s_setprio(0); } while (0)
; #define PG8_WAIT_V(n) asm volatile("s_waitcnt vmcnt(" #n ")" ::: "memory")
; #define PG8_WAIT_L(n) asm volatile("s_waitcnt lgkmcnt(" #n ")" ::: "memory")
; #define PG8_BAR __builtin_amdgcn_s_barrier()
; #define PG8_SCHED __builtin_amdgcn_sched_barrier(0)
; template <class Epi, class Sched, bool ALIGN_EPI = false, bool SP2 = false>
; __device__ __forceinline__ void gemm_phase(PG8_LAS unsigned char* lds, const int tid, const Gemm g, const Sched& S, const Epi& E) {
;     ...
;             PG8_WAIT_V(8); PG8_WAIT_L(0); PG8_BAR; PG8_MMA(0, 0, At, B0); PG8_MMA(0, 1, At, B1); PG8_BAR; PG8_SCHED;
;             PG8_LDA(At, 0, 1); PG8_STAGE(PG8_SB(0, 0), b2, voffB); PG8_STAGE(PG8_SB(0, 1), b2 + hstep, voffB); PG8_STAGE(PG8_SA(0, 0), a2, voffA);
;             PG8_WAIT_V(8); PG8_WAIT_L(0); PG8_BAR; PG8_MMA(1, 0, At, B0); PG8_MMA(1, 1, At, B1); PG8_BAR; PG8_SCHED;
;             PG8_LDB(B0, 1, 0); PG8_LDB(B1, 1, 1); PG8_SCHED; PG8_LDA(At, 1, 0); PG8_STAGE(PG8_SA(0, 1), a2 + hstep, voffA);
;             PG8_WAIT_V(8); PG8_WAIT_L(0); PG8_BAR; PG8_MMA(0, 0, At, B0); PG8_MMA(0, 1, At, B1); PG8_BAR; PG8_SCHED;
	s_setprio 1
	s_waitcnt lgkmcnt(0)
	v_mfma_f32_16x16x32_bf16 v[60:63], v[72:75], v[160:163], 0
	v_mfma_f32_16x16x32_bf16 v[56:59], v[136:139], v[160:163], 0
	v_mfma_f32_16x16x32_bf16 v[44:47], v[72:75], v[196:199], 0
	v_mfma_f32_16x16x32_bf16 v[40:43], v[136:139], v[196:199], 0
	v_mfma_f32_16x16x32_bf16 v[28:31], v[72:75], v[204:207], 0
	v_mfma_f32_16x16x32_bf16 v[24:27], v[136:139], v[204:207], 0
	v_mfma_f32_16x16x32_bf16 v[12:15], v[72:75], v[212:215], 0
	v_mfma_f32_16x16x32_bf16 v[8:11], v[136:139], v[212:215], 0
	v_mfma_f32_16x16x32_bf16 v[60:63], v[76:79], v[164:167], v[60:63]
	v_mfma_f32_16x16x32_bf16 v[56:59], v[140:143], v[164:167], v[56:59]
	v_mfma_f32_16x16x32_bf16 v[44:47], v[76:79], v[200:203], v[44:47]
	v_mfma_f32_16x16x32_bf16 v[40:43], v[140:143], v[200:203], v[40:43]
	v_mfma_f32_16x16x32_bf16 v[28:31], v[76:79], v[208:211], v[28:31]
	v_mfma_f32_16x16x32_bf16 v[24:27], v[140:143], v[208:211], v[24:27]
	v_mfma_f32_16x16x32_bf16 v[12:15], v[76:79], v[216:219], v[12:15]
	v_mfma_f32_16x16x32_bf16 v[8:11], v[140:143], v[216:219], v[8:11]
	s_setprio 0
	s_setprio 1
	v_mfma_f32_16x16x32_bf16 v[52:55], v[144:147], v[160:163], 0
	v_mfma_f32_16x16x32_bf16 v[48:51], v[152:155], v[160:163], 0
	v_mfma_f32_16x16x32_bf16 v[36:39], v[144:147], v[196:199], 0
	v_mfma_f32_16x16x32_bf16 v[32:35], v[152:155], v[196:199], 0
	v_mfma_f32_16x16x32_bf16 v[20:23], v[144:147], v[204:207], 0
	v_mfma_f32_16x16x32_bf16 v[16:19], v[152:155], v[204:207], 0
	v_mfma_f32_16x16x32_bf16 v[4:7], v[144:147], v[212:215], 0
	v_mfma_f32_16x16x32_bf16 v[0:3], v[152:155], v[212:215], 0
	v_mfma_f32_16x16x32_bf16 v[52:55], v[148:151], v[164:167], v[52:55]
	v_mfma_f32_16x16x32_bf16 v[48:51], v[156:159], v[164:167], v[48:51]
	v_mfma_f32_16x16x32_bf16 v[36:39], v[148:151], v[200:203], v[36:39]
	v_mfma_f32_16x16x32_bf16 v[32:35], v[156:159], v[200:203], v[32:35]
	v_mfma_f32_16x16x32_bf16 v[20:23], v[148:151], v[208:211], v[20:23]
	v_mfma_f32_16x16x32_bf16 v[16:19], v[156:159], v[208:211], v[16:19]
	v_mfma_f32_16x16x32_bf16 v[4:7], v[148:151], v[216:219], v[4:7]
	v_mfma_f32_16x16x32_bf16 v[0:3], v[156:159], v[216:219], v[0:3]
	s_setprio 0
	s_barrier
	ds_read_b128 v[72:75], v247 offset:32768
	ds_read_b128 v[76:79], v248 offset:32768
	ds_read_b128 v[136:139], v247 offset:34816
	ds_read_b128 v[140:143], v248 offset:34816
	ds_read_b128 v[144:147], v247 offset:49152
	ds_read_b128 v[148:151], v248 offset:49152
	ds_read_b128 v[152:155], v247 offset:51200
	ds_read_b128 v[156:159], v248 offset:51200
	s_add_u32 s24, s24, s12
	s_addc_u32 s25, s25, 0
	s_mov_b32 m0, s22
	ds_read_b128 v[160:163], v232 offset:32768
	ds_read_b128 v[164:167], v246 offset:32768
	ds_read_b128 v[196:199], v232 offset:34816
	ds_read_b128 v[200:203], v246 offset:34816
	ds_read_b128 v[204:207], v232 offset:36864
	ds_read_b128 v[208:211], v246 offset:36864
	ds_read_b128 v[212:215], v232 offset:38912
	ds_read_b128 v[216:219], v246 offset:38912
	global_load_lds_dwordx4 v190, s[24:25]
	s_mov_b32 m0, s23
	s_nop 0
	global_load_lds_dwordx4 v188, s[24:25]
	s_waitcnt vmcnt(8)
	s_waitcnt lgkmcnt(0)
	s_barrier
	s_setprio 1
	s_waitcnt lgkmcnt(0)
	v_mfma_f32_16x16x32_bf16 v[132:135], v[72:75], v[160:163], v[132:135]
	v_mfma_f32_16x16x32_bf16 v[128:131], v[136:139], v[160:163], v[128:131]
	v_mfma_f32_16x16x32_bf16 v[116:119], v[72:75], v[196:199], v[116:119]
	v_mfma_f32_16x16x32_bf16 v[112:115], v[136:139], v[196:199], v[112:115]
	v_mfma_f32_16x16x32_bf16 v[100:103], v[72:75], v[204:207], v[100:103]
	v_mfma_f32_16x16x32_bf16 v[96:99], v[136:139], v[204:207], v[96:99]
	v_mfma_f32_16x16x32_bf16 v[84:87], v[72:75], v[212:215], v[84:87]
	v_mfma_f32_16x16x32_bf16 v[80:83], v[136:139], v[212:215], v[80:83]
	v_mfma_f32_16x16x32_bf16 v[132:135], v[76:79], v[164:167], v[132:135]
	v_mfma_f32_16x16x32_bf16 v[128:131], v[140:143], v[164:167], v[128:131]
	v_mfma_f32_16x16x32_bf16 v[116:119], v[76:79], v[200:203], v[116:119]
	v_mfma_f32_16x16x32_bf16 v[112:115], v[140:143], v[200:203], v[112:115]
	v_mfma_f32_16x16x32_bf16 v[100:103], v[76:79], v[208:211], v[100:103]
	v_mfma_f32_16x16x32_bf16 v[96:99], v[140:143], v[208:211], v[96:99]
	v_mfma_f32_16x16x32_bf16 v[84:87], v[76:79], v[216:219], v[84:87]
	v_mfma_f32_16x16x32_bf16 v[80:83], v[140:143], v[216:219], v[80:83]
	s_setprio 0
	s_setprio 1
	v_mfma_f32_16x16x32_bf16 v[124:127], v[144:147], v[160:163], v[124:127]
	v_mfma_f32_16x16x32_bf16 v[120:123], v[152:155], v[160:163], v[120:123]
	v_mfma_f32_16x16x32_bf16 v[108:111], v[144:147], v[196:199], v[108:111]
	v_mfma_f32_16x16x32_bf16 v[104:107], v[152:155], v[196:199], v[104:107]
	v_mfma_f32_16x16x32_bf16 v[92:95], v[144:147], v[204:207], v[92:95]
	v_mfma_f32_16x16x32_bf16 v[88:91], v[152:155], v[204:207], v[88:91]
	v_mfma_f32_16x16x32_bf16 v[68:71], v[144:147], v[212:215], v[68:71]
	v_mfma_f32_16x16x32_bf16 v[64:67], v[152:155], v[212:215], v[64:67]
	v_mfma_f32_16x16x32_bf16 v[124:127], v[148:151], v[164:167], v[124:127]
	v_mfma_f32_16x16x32_bf16 v[120:123], v[156:159], v[164:167], v[120:123]
	v_mfma_f32_16x16x32_bf16 v[108:111], v[148:151], v[200:203], v[108:111]
	v_mfma_f32_16x16x32_bf16 v[104:107], v[156:159], v[200:203], v[104:107]
	v_mfma_f32_16x16x32_bf16 v[92:95], v[148:151], v[208:211], v[92:95]
	v_mfma_f32_16x16x32_bf16 v[88:91], v[156:159], v[208:211], v[88:91]
	v_mfma_f32_16x16x32_bf16 v[68:71], v[148:151], v[216:219], v[68:71]
	v_mfma_f32_16x16x32_bf16 v[64:67], v[156:159], v[216:219], v[64:67]
	s_setprio 0
	s_barrier
; #define PG8_STAGE(bufoff, gbase, voff) do { _Pragma("unroll") for (int _i = 0; _i < 2; ++_i) \
;         __builtin_amdgcn_global_load_lds((const unsigned*)((const char*)(gbase) + (voff)[_i]), (PG8_LAS unsigned*)(lds + (bufoff) + ldsw + _i * 8192), 16, 0, 0); } while (0)
; #define PG8_LDA(dst, b, h) do { _Pragma("unroll") for (int m = 0; m < 4; ++m) _Pragma("unroll") for (int k = 0; k < 2; ++k) dst[m][k] = *(const PG8_LAS bf16x8*)(lds + PG8_SA(b, h) + aoff + m * 2048 + k * 1024); } while (0)
; #define PG8_MMA(ai, bj, At, Bt) do { __builtin_amdgcn_s_setprio(1); _Pragma("unroll") for (int m = 0; m < 4; ++m) _Pragma("unroll") for (int n = 0; n < 2; ++n) _Pragma("unroll") for (int k = 0; k < 2; ++k) \
;         acc[ai][bj][m][n] = __builtin_amdgcn_mfma_f32_16x16x32_bf16(Bt[n][k], At[m][k], acc[ai][bj][m][n], 0, 0, 0); __builtin_amdgcn_s_setprio(0); } while (0)
; #define PG8_WAIT_V(n) asm volatile("s_waitcnt vmcnt(" #n ")" ::: "memory")
; #define PG8_WAIT_L(n) asm volatile("s_waitcnt lgkmcnt(" #n ")" ::: "memory")
; #define PG8_BAR __builtin_amdgcn_s_barrier()
; #define PG8_SCHED __builtin_amdgcn_sched_barrier(0)
; template <class Epi, class Sched, bool ALIGN_EPI = false, bool SP2 = false>
; __device__ __forceinline__ void gemm_phase(PG8_LAS unsigned char* lds, const int tid, const Gemm g, const Sched& S, const Epi& E) {
;     ...
;             PG8_LDA(At, 1, 1); PG8_STAGE(PG8_SB(1, 0), b3, voffB); PG8_STAGE(PG8_SB(1, 1), b3 + hstep, voffB); PG8_STAGE(PG8_SA(1, 0), a3, voffA);
;             PG8_WAIT_V(8); PG8_WAIT_L(0); PG8_BAR; PG8_MMA(1, 0, At, B0); PG8_MMA(1, 1, At, B1); PG8_BAR; PG8_SCHED;
	s_add_u32 s96, s52, 0x80
	s_addc_u32 s97, s53, 0
	s_add_i32 m0, s15, 0x18000
	ds_read_b128 v[160:163], v232 offset:49152
	ds_read_b128 v[164:167], v246 offset:49152
	ds_read_b128 v[196:199], v232 offset:51200
	ds_read_b128 v[200:203], v246 offset:51200
	ds_read_b128 v[204:207], v232 offset:53248
	ds_read_b128 v[208:211], v246 offset:53248
	ds_read_b128 v[212:215], v232 offset:55296
	ds_read_b128 v[216:219], v246 offset:55296
	global_load_lds_dwordx4 v168, s[94:95]
	s_add_i32 m0, s15, 0x1a000
	s_nop 0
	global_load_lds_dwordx4 v186, s[94:95]
	s_add_i32 m0, s15, 0x1c000
	s_nop 0
	global_load_lds_dwordx4 v168, s[96:97]
	s_add_i32 m0, s15, 0x1e000
	s_nop 0
	global_load_lds_dwordx4 v186, s[96:97]
	s_mov_b32 m0, s45
	s_nop 0
	global_load_lds_dwordx4 v190, s[98:99]
	s_mov_b32 m0, s46
	s_nop 0
	global_load_lds_dwordx4 v188, s[98:99]
	s_waitcnt vmcnt(8)
	s_waitcnt lgkmcnt(0)
	s_barrier
	s_setprio 1
	s_waitcnt lgkmcnt(0)
	v_mfma_f32_16x16x32_bf16 v[60:63], v[72:75], v[160:163], v[60:63]
	v_mfma_f32_16x16x32_bf16 v[56:59], v[136:139], v[160:163], v[56:59]
	v_mfma_f32_16x16x32_bf16 v[44:47], v[72:75], v[196:199], v[44:47]
	v_mfma_f32_16x16x32_bf16 v[40:43], v[136:139], v[196:199], v[40:43]
	v_mfma_f32_16x16x32_bf16 v[28:31], v[72:75], v[204:207], v[28:31]
	v_mfma_f32_16x16x32_bf16 v[24:27], v[136:139], v[204:207], v[24:27]
	v_mfma_f32_16x16x32_bf16 v[12:15], v[72:75], v[212:215], v[12:15]
	v_mfma_f32_16x16x32_bf16 v[8:11], v[136:139], v[212:215], v[8:11]
	v_mfma_f32_16x16x32_bf16 v[60:63], v[76:79], v[164:167], v[60:63]
	v_mfma_f32_16x16x32_bf16 v[56:59], v[140:143], v[164:167], v[56:59]
	v_mfma_f32_16x16x32_bf16 v[44:47], v[76:79], v[200:203], v[44:47]
	v_mfma_f32_16x16x32_bf16 v[40:43], v[140:143], v[200:203], v[40:43]
	v_mfma_f32_16x16x32_bf16 v[28:31], v[76:79], v[208:211], v[28:31]
	v_mfma_f32_16x16x32_bf16 v[24:27], v[140:143], v[208:211], v[24:27]
	v_mfma_f32_16x16x32_bf16 v[12:15], v[76:79], v[216:219], v[12:15]
	v_mfma_f32_16x16x32_bf16 v[8:11], v[140:143], v[216:219], v[8:11]
	s_setprio 0
	s_setprio 1
	v_mfma_f32_16x16x32_bf16 v[52:55], v[144:147], v[160:163], v[52:55]
	v_mfma_f32_16x16x32_bf16 v[48:51], v[152:155], v[160:163], v[48:51]
	v_mfma_f32_16x16x32_bf16 v[36:39], v[144:147], v[196:199], v[36:39]
	v_mfma_f32_16x16x32_bf16 v[32:35], v[152:155], v[196:199], v[32:35]
	v_mfma_f32_16x16x32_bf16 v[20:23], v[144:147], v[204:207], v[20:23]
	v_mfma_f32_16x16x32_bf16 v[16:19], v[152:155], v[204:207], v[16:19]
	v_mfma_f32_16x16x32_bf16 v[4:7], v[144:147], v[212:215], v[4:7]
	v_mfma_f32_16x16x32_bf16 v[0:3], v[152:155], v[212:215], v[0:3]
	v_mfma_f32_16x16x32_bf16 v[52:55], v[148:151], v[164:167], v[52:55]
	v_mfma_f32_16x16x32_bf16 v[48:51], v[156:159], v[164:167], v[48:51]
	v_mfma_f32_16x16x32_bf16 v[36:39], v[148:151], v[200:203], v[36:39]
	v_mfma_f32_16x16x32_bf16 v[32:35], v[156:159], v[200:203], v[32:35]
	v_mfma_f32_16x16x32_bf16 v[20:23], v[148:151], v[208:211], v[20:23]
	v_mfma_f32_16x16x32_bf16 v[16:19], v[156:159], v[208:211], v[16:19]
	v_mfma_f32_16x16x32_bf16 v[4:7], v[148:151], v[216:219], v[4:7]
	v_mfma_f32_16x16x32_bf16 v[0:3], v[156:159], v[216:219], v[0:3]
	s_setprio 0
	s_barrier
	s_add_u32 s38, s38, 0x100
	s_addc_u32 s39, s39, 0
	s_add_u32 s26, s26, 0x100
	s_addc_u32 s27, s27, 0
	s_cmp_ge_u32 s51, s44
	s_mov_b32 s14, s51
	s_cbranch_scc0 .LBB0_311
	s_branch .Lpeel_exit_g2

; #define PG8_GAS __attribute__((address_space(1)))
;     __device__ __forceinline__ void operator()(const f32x4 (&acc)[2][2][4][2], const Unit& u, int wr, int wc, int fr, int fq) const {
;     ...
;         const PG8_GAS bf16_t* xinb = (const PG8_GAS bf16_t*)pp->xinb; PG8_GAS float* out = (PG8_GAS float*)pp->out; PG8_GAS bf16_t* outb = (PG8_GAS bf16_t*)pp->outb; const PG8_GAS float* gate = (const PG8_GAS float*)pp->gate;
;         PG8_GAS float* rss = (PG8_GAS float*)pp->rss; const float gs = pp->gs; const int flags = pp->flags; const bool has = flags & 1, outf = flags & 4;
;         const int b = (u.pm * BM) >> 13;
;         const PG8_GAS float* gp = gate + (size_t)b * 9216;
;         const int row0 = u.pm * BM + wr * 64 + fr, col0 = u.pn * BM + wc * 32 + 8 * fq;
;         f32x4 gv[2][2];
; #pragma unroll
;         for (int bj = 0; bj < 2; ++bj)
; #pragma unroll
;             for (int n = 0; n < 2; ++n) gv[bj][n] = *(const PG8_GAS f32x4*)(gp + col0 + bj * HALF + n * 4) * gs;
; #pragma unroll
;         for (int ai = 0; ai < 2; ++ai) {
;             u32x4 xa[2][4][2];
; #pragma unroll
;             for (int m = 0; m < 4; ++m)
; #pragma unroll
;                 for (int bj = 0; bj < 2; ++bj) xa[ai][m][bj] = *(const PG8_GAS u32x4*)(xinb + (size_t)(row0 + ai * HALF + m * 16) * 1024 + col0 + bj * HALF);
; #pragma unroll
;             for (int m = 0; m < 4; ++m) { const int row = row0 + ai * HALF + m * 16; const size_t off = (size_t)row * 1024 + col0; float ss = 0.f;
; #pragma unroll
;                 for (int bj = 0; bj < 2; ++bj) {
;                     const u32x4 t = xa[ai][m][bj];
;                     const f32x4 x0 = (f32x4){__uint_as_float(t.x << 16), __uint_as_float(t.x & 0xffff0000u), __uint_as_float(t.y << 16), __uint_as_float(t.y & 0xffff0000u)};
;                     const f32x4 x1 = (f32x4){__uint_as_float(t.z << 16), __uint_as_float(t.z & 0xffff0000u), __uint_as_float(t.w << 16), __uint_as_float(t.w & 0xffff0000u)};
;                     const f32x4 o0 = x0 + gv[bj][0] * acc[ai][bj][m][0], o1 = x1 + gv[bj][1] * acc[ai][bj][m][1];
;                     if (outf) { *(PG8_GAS f32x4*)(out + off + bj * HALF) = o0; *(PG8_GAS f32x4*)(out + off + bj * HALF + 4) = o1; }
.LBB0_314:
	v_readlane_b32 s10, v251, 33
	v_lshl_or_b32 v200, s41, 8, v231
	v_ashrrev_i32_e32 v201, 31, v200
	v_mov_b32_e32 v76, s10
	v_readlane_b32 s10, v251, 34
	v_lshl_add_u32 v196, s40, 8, v183
	v_ashrrev_i32_e32 v197, 31, v196
	v_mov_b32_e32 v72, s10
	ds_read_b128 v[72:75], v72
	ds_read_b128 v[76:79], v76
	s_ashr_i32 s10, s40, 5
	s_mul_hi_i32 s25, s10, 0x9000
	s_mul_i32 s24, s10, 0x9000
	s_waitcnt lgkmcnt(0)
	v_lshl_add_u64 v[74:75], v[74:75], 0, s[24:25]
	v_lshl_add_u64 v[74:75], v[200:201], 2, v[74:75]
	global_load_dwordx4 v[202:205], v[74:75], off offset:16
	global_load_dwordx4 v[206:209], v[74:75], off
	global_load_dwordx4 v[156:159], v[74:75], off offset:528
	global_load_dwordx4 v[164:167], v[74:75], off offset:512
	v_lshl_add_u64 v[210:211], v[200:201], 1, v[76:77]
	v_lshlrev_b64 v[74:75], 11, v[196:197]
	v_or_b32_e32 v216, 16, v196
	v_lshl_add_u64 v[74:75], v[210:211], 0, v[74:75]
	v_ashrrev_i32_e32 v217, 31, v216
	global_load_dwordx4 v[234:237], v[74:75], off
	global_load_dwordx4 v[160:163], v[74:75], off offset:256
	v_lshlrev_b64 v[74:75], 11, v[216:217]
	v_or_b32_e32 v214, 32, v196
	v_lshl_add_u64 v[74:75], v[210:211], 0, v[74:75]
	v_ashrrev_i32_e32 v215, 31, v214
	global_load_dwordx4 v[152:155], v[74:75], off
	global_load_dwordx4 v[148:151], v[74:75], off offset:256
	v_lshlrev_b64 v[74:75], 11, v[214:215]
	v_or_b32_e32 v212, 48, v196
	v_lshl_add_u64 v[74:75], v[210:211], 0, v[74:75]
	v_ashrrev_i32_e32 v213, 31, v212
	global_load_dwordx4 v[144:147], v[74:75], off
	global_load_dwordx4 v[140:143], v[74:75], off offset:256
	v_lshlrev_b64 v[74:75], 11, v[212:213]
	v_lshl_add_u64 v[74:75], v[210:211], 0, v[74:75]
	global_load_dwordx4 v[136:139], v[74:75], off
	s_nop 0
	global_load_dwordx4 v[74:77], v[74:75], off offset:256
	v_add_u32_e32 v254, 0x80, v196
	v_ashrrev_i32_e32 v255, 31, v254
	v_lshlrev_b64 v[254:255], 11, v[254:255]
	v_lshl_add_u64 v[254:255], v[210:211], 0, v[254:255]
	global_load_dwordx4 v[242:245], v[254:255], off
	global_load_dwordx4 v[246:249], v[254:255], off offset:256
	v_readlane_b32 s10, v251, 36
	v_lshlrev_b64 v[220:221], 10, v[196:197]
	v_lshl_add_u64 v[220:221], v[220:221], 0, v[200:201]
	v_mov_b32_e32 v198, s10
	ds_read_b64 v[218:219], v198
	v_readlane_b32 s10, v251, 35
	s_mov_b64 s[38:39], -1
	v_readlane_b32 s14, v251, 49
	v_mov_b32_e32 v198, s10
	ds_read_b64 v[198:199], v198
	s_waitcnt lgkmcnt(0)
	v_readfirstlane_b32 s25, v219
	v_readfirstlane_b32 s24, v218
	s_and_b32 s10, s25, 4
	s_bitcmp1_b32 s25, 2
	v_lshl_add_u64 v[218:219], v[220:221], 2, v[78:79]
	s_cselect_b64 s[26:27], -1, 0
	s_cmp_eq_u32 s10, 0
	s_waitcnt vmcnt(0)
	v_pk_mul_f32 v[204:205], s[24:25], v[204:205] op_sel_hi:[0,1]
	v_pk_mul_f32 v[208:209], s[24:25], v[208:209] op_sel_hi:[0,1]
	v_pk_mul_f32 v[206:207], s[24:25], v[206:207] op_sel_hi:[0,1]
	v_pk_mul_f32 v[202:203], s[24:25], v[202:203] op_sel_hi:[0,1]
	v_lshlrev_b32_e32 v238, 16, v234
	v_and_b32_e32 v239, 0xffff0000, v234
	v_lshlrev_b32_e32 v234, 16, v235
	v_and_b32_e32 v235, 0xffff0000, v235
	v_lshlrev_b32_e32 v240, 16, v236
	v_and_b32_e32 v241, 0xffff0000, v236
	v_lshlrev_b32_e32 v236, 16, v237
	v_and_b32_e32 v237, 0xffff0000, v237
	v_pk_fma_f32 v[134:135], v[134:135], v[208:209], v[234:235]
	v_pk_fma_f32 v[132:133], v[132:133], v[206:207], v[238:239]
	v_pk_fma_f32 v[130:131], v[130:131], v[204:205], v[236:237]
	v_pk_fma_f32 v[128:129], v[128:129], v[202:203], v[240:241]
	s_cbranch_scc1 .LBB0_316
	s_mov_b64 s[38:39], 0
	global_store_dwordx4 v[218:219], v[132:135], off
	global_store_dwordx4 v[218:219], v[128:131], off offset:16

; #define PG8_GAS __attribute__((address_space(1)))
;     __device__ __forceinline__ void operator()(const f32x4 (&acc)[2][2][4][2], const Unit& u, int wr, int wc, int fr, int fq) const {
;     ...
;                 for (int bj = 0; bj < 2; ++bj) xa[ai][m][bj] = *(const PG8_GAS u32x4*)(xinb + (size_t)(row0 + ai * HALF + m * 16) * 1024 + col0 + bj * HALF);
; #pragma unroll
;             for (int m = 0; m < 4; ++m) { const int row = row0 + ai * HALF + m * 16; const size_t off = (size_t)row * 1024 + col0; float ss = 0.f;
; #pragma unroll
;                 for (int bj = 0; bj < 2; ++bj) {
;                     const u32x4 t = xa[ai][m][bj];
;                     const f32x4 x0 = (f32x4){__uint_as_float(t.x << 16), __uint_as_float(t.x & 0xffff0000u), __uint_as_float(t.y << 16), __uint_as_float(t.y & 0xffff0000u)};
;                     const f32x4 x1 = (f32x4){__uint_as_float(t.z << 16), __uint_as_float(t.z & 0xffff0000u), __uint_as_float(t.w << 16), __uint_as_float(t.w & 0xffff0000u)};
;                     const f32x4 o0 = x0 + gv[bj][0] * acc[ai][bj][m][0], o1 = x1 + gv[bj][1] * acc[ai][bj][m][1];
.LBB0_362:
	v_add_u32_e32 v102, 0x80, v196
	v_ashrrev_i32_e32 v103, 31, v102
	s_waitcnt lgkmcnt(0)
	v_lshlrev_b64 v[64:65], 11, v[102:103]
	v_add_u32_e32 v100, 0x90, v196
	v_lshl_add_u64 v[64:65], v[210:211], 0, v[64:65]
	v_ashrrev_i32_e32 v101, 31, v100
	v_lshlrev_b64 v[64:65], 11, v[100:101]
	v_add_u32_e32 v98, 0xa0, v196
	v_lshl_add_u64 v[64:65], v[210:211], 0, v[64:65]
	v_ashrrev_i32_e32 v99, 31, v98
	global_load_dwordx4 v[88:91], v[64:65], off
	global_load_dwordx4 v[84:87], v[64:65], off offset:256
	v_lshlrev_b64 v[64:65], 11, v[98:99]
	v_add_u32_e32 v96, 0xb0, v196
	v_lshl_add_u64 v[64:65], v[210:211], 0, v[64:65]
	v_ashrrev_i32_e32 v97, 31, v96
	global_load_dwordx4 v[80:83], v[64:65], off
	global_load_dwordx4 v[74:77], v[64:65], off offset:256
	v_lshlrev_b64 v[64:65], 11, v[96:97]
	v_lshl_add_u64 v[64:65], v[210:211], 0, v[64:65]
	global_load_dwordx4 v[68:71], v[64:65], off
	s_nop 0
	global_load_dwordx4 v[64:67], v[64:65], off offset:256
	v_lshlrev_b64 v[102:103], 10, v[102:103]
	v_lshl_add_u64 v[104:105], v[102:103], 0, v[200:201]
	s_and_b64 vcc, exec, s[38:39]
	v_lshl_add_u64 v[102:103], v[104:105], 2, v[78:79]
	s_mov_b64 s[24:25], -1
	v_lshlrev_b32_e32 v110, 16, v242
	v_and_b32_e32 v111, 0xffff0000, v242
	v_lshlrev_b32_e32 v106, 16, v243
	v_and_b32_e32 v107, 0xffff0000, v243
	v_lshlrev_b32_e32 v112, 16, v244
	v_and_b32_e32 v113, 0xffff0000, v244
	v_lshlrev_b32_e32 v108, 16, v245
	v_and_b32_e32 v109, 0xffff0000, v245
	v_pk_fma_f32 v[62:63], v[62:63], v[208:209], v[106:107]
	v_pk_fma_f32 v[60:61], v[60:61], v[206:207], v[110:111]
	v_pk_fma_f32 v[58:59], v[58:59], v[204:205], v[108:109]
	v_pk_fma_f32 v[56:57], v[56:57], v[202:203], v[112:113]
	s_cbranch_vccnz .LBB0_364
	s_mov_b64 s[24:25], 0
	global_store_dwordx4 v[102:103], v[60:63], off
	global_store_dwordx4 v[102:103], v[56:59], off offset:16

;     __device__ __forceinline__ void operator()(const f32x4 (&acc)[2][2][4][2], const Unit& u, int wr, int wc, int fr, int fq) const {
;     ...
;                     const u32x4 t = xa[ai][m][bj];
;                     const f32x4 x0 = (f32x4){__uint_as_float(t.x << 16), __uint_as_float(t.x & 0xffff0000u), __uint_as_float(t.y << 16), __uint_as_float(t.y & 0xffff0000u)};
;                     const f32x4 x1 = (f32x4){__uint_as_float(t.z << 16), __uint_as_float(t.z & 0xffff0000u), __uint_as_float(t.w << 16), __uint_as_float(t.w & 0xffff0000u)};
;                     const f32x4 o0 = x0 + gv[bj][0] * acc[ai][bj][m][0], o1 = x1 + gv[bj][1] * acc[ai][bj][m][1];
.LBB0_366:
	s_nop 1
	v_lshlrev_b32_e32 v106, 16, v246
	v_and_b32_e32 v107, 0xffff0000, v246
	v_lshlrev_b32_e32 v92, 16, v247
	v_and_b32_e32 v93, 0xffff0000, v247
	v_lshlrev_b32_e32 v108, 16, v248
	v_and_b32_e32 v109, 0xffff0000, v248
	v_lshlrev_b32_e32 v94, 16, v249
	v_and_b32_e32 v95, 0xffff0000, v249
	v_pk_fma_f32 v[54:55], v[54:55], v[166:167], v[92:93]
	v_pk_fma_f32 v[52:53], v[52:53], v[164:165], v[106:107]
	v_pk_fma_f32 v[50:51], v[50:51], v[158:159], v[94:95]
	v_pk_fma_f32 v[48:49], v[48:49], v[156:157], v[108:109]
	s_and_b64 vcc, exec, s[38:39]
	s_mov_b64 s[24:25], -1
	s_cbranch_vccz .LBB0_369
	s_andn2_b64 vcc, exec, s[24:25]
	s_cbranch_vccz .LBB0_370

; #define PG8_WAIT_V(n) asm volatile("s_waitcnt vmcnt(" #n ")" ::: "memory")
; #define PG8_BAR __builtin_amdgcn_s_barrier()
; template <class Epi, class Sched, bool ALIGN_EPI = false, bool SP2 = false>
; __device__ __forceinline__ void gemm_phase(PG8_LAS unsigned char* lds, const int tid, const Gemm g, const Sched& S, const Epi& E) {
;     const int wid = __builtin_amdgcn_readfirstlane(tid >> 6), lane = tid & 63, wr = wid >> 2, wc = wid & 3, fr = lane & 15, fq = lane >> 4;
;     const int K = g.K, nt = K / BK;
;     unsigned voffA[2], voffB[2];
; #pragma unroll
;     for (int i = 0; i < 2; ++i) { int R, C; stage_rc(tid * 16 + i * 8192, R, C); const int Rb = Epi::PERM ? ((R & ~31) + perm32(R & 31)) : R;
;         voffA[i] = (unsigned)(R * K + C) * 2u; voffB[i] = (unsigned)(Rb * K + C) * 2u; }
;     const size_t kstep = (size_t)(BK * 2);
;     const size_t hstep = (size_t)HALF * K * 2;
;     const size_t tstep = 2 * hstep;
;     const unsigned ldsw = (unsigned)wid * 1024u;
;     const int aoff = lds_byte(wr * 64 + fr, fq * 8), boff = lds_byte(wc * 32 + fr, fq * 8);
;     ...
;     Unit cur, nxt; int ui = 0;
;     if (!S.next(0, cur)) return;
;     f32x4 acc[2][2][4][2];
; #pragma unroll
;     for (int a = 0; a < 2; ++a)
; #pragma unroll
;         for (int b = 0; b < 2; ++b)
; #pragma unroll
;             for (int m = 0; m < 4; ++m)
; #pragma unroll
;                 for (int n = 0; n < 2; ++n) acc[a][b][m][n] = (f32x4){0.f, 0.f, 0.f, 0.f};
;     bf16x8 At[4][2], B0[2][2], B1[2][2];
;     const char* cA = (const char*)g.A + (size_t)cur.pm * tstep; const char* cB = (const char*)g.Bt + (size_t)cur.pn * tstep + (size_t)(cur.pm >> 5) * g.bstride;
;     S.a_ready(cur);
;     if constexpr (SP2) {
;         PG8_STAGE(PG8_SB(0, 0), cB, voffB); PG8_STAGE(PG8_SB(0, 1), cB + hstep, voffB); PG8_STAGE(PG8_SA(0, 0), cA, voffA); PG8_STAGE(PG8_SA(0, 1), cA + hstep, voffA);
;         if (wr == 1) PG8_BAR;
;         PG8_WAIT_V(2); PG8_BAR;
;         PG8_STAGE(PG8_SB(1, 0), cB + kstep, voffB); PG8_STAGE(PG8_SA(1, 0), cA + kstep, voffA); PG8_STAGE(PG8_SB(1, 1), cB + hstep + kstep, voffB);
;         PG8_WAIT_V(6); PG8_BAR;
;     } else {
;         PG8_STAGE(PG8_SB(0, 0), cB, voffB); PG8_STAGE(PG8_SA(0, 0), cA, voffA); PG8_STAGE(PG8_SB(0, 1), cB + hstep, voffB); PG8_STAGE(PG8_SA(0, 1), cA + hstep, voffA);
;         if (wr == 1) PG8_BAR;
.LBB0_414:
	s_and_b64 vcc, exec, s[0:1]
	s_cbranch_vccz .LBB0_433
	v_readlane_b32 s0, v252, 24
	v_readlane_b32 s1, v252, 25
	s_andn2_b64 vcc, exec, s[0:1]
	v_readfirstlane_b32 s4, v184
	s_cbranch_vccnz .LBB0_433
	v_lshrrev_b32_e32 v236, 3, v182
	v_and_b32_e32 v237, 6, v236
	v_and_b32_e32 v238, 7, v182
	v_xor_b32_e32 v238, v238, v237
	v_lshlrev_b32_e32 v238, 4, v238
	s_lshr_b32 s90, s4, 6
	s_lshl_b32 s91, s90, 3
	v_add_u32_e32 v239, s91, v236
	v_lshl_add_u32 v244, v239, 11, v238
	v_add_u32_e32 v245, 0x20000, v244
	v_and_b32_e32 v240, 31, v239
	v_bfe_u32 v241, v240, 2, 2
	v_lshlrev_b32_e32 v241, 3, v241
	v_bfe_u32 v242, v240, 4, 1
	v_lshl_or_b32 v241, v242, 2, v241
	v_and_b32_e32 v242, 3, v240
	v_or_b32_e32 v241, v241, v242
	v_and_b32_e32 v242, 32, v239
	v_or_b32_e32 v241, v241, v242
	v_lshl_add_u32 v246, v241, 11, v238
	v_add_u32_e32 v247, 0x20000, v246
	v_and_b32_e32 v236, 15, v182
	v_lshrrev_b32_e32 v237, 4, v182
	v_and_b32_e32 v239, 6, v236
	v_xor_b32_e32 v237, v237, v239
	v_lshlrev_b32_e32 v237, 4, v237
	v_and_b32_e32 v239, 7, v236
	v_lshl_or_b32 v237, v239, 7, v237
	v_bfe_u32 v239, v236, 3, 1
	v_lshl_or_b32 v237, v239, 10, v237
	s_lshr_b32 s92, s4, 8
	s_lshl_b32 s92, s92, 13
	v_add_u32_e32 v248, s92, v237
	v_xor_b32_e32 v249, 64, v248
	s_bfe_u32 s93, s4, 0x20006
	s_lshl_b32 s93, s93, 12
	v_add_u32_e32 v254, s93, v237
	v_xor_b32_e32 v255, 64, v254
	v_lshlrev_b32_e32 v234, 4, v182
	v_lshlrev_b32_e32 v0, 4, v184
	s_waitcnt lgkmcnt(0)
	v_add_u32_e32 v1, 0x2000, v0
	v_ashrrev_i32_e32 v2, 31, v1
	v_lshrrev_b32_e32 v2, 22, v2
	v_add_u32_e32 v2, v1, v2
	v_ashrrev_i32_e32 v8, 10, v2
	v_mul_i32_i24_e32 v2, 0x400, v8
	v_sub_u32_e32 v1, v1, v2
	v_lshrrev_b32_e32 v2, 4, v1
	v_bitop3_b32 v1, v2, v1, 32 bitop3:0x6c
	s_cmp_eq_u32 s7, 6
	v_ashrrev_i32_e32 v2, 31, v1
	s_cselect_b64 s[0:1], -1, 0
	v_lshrrev_b32_e32 v2, 26, v2
	s_and_b64 s[2:3], s[0:1], exec
	v_add_u32_e32 v2, v1, v2
	v_lshlrev_b32_e32 v3, 3, v8
	s_cselect_b32 s2, 0x2c00000, 0
	v_readlane_b32 s3, v251, 50
	v_ashrrev_i32_e32 v9, 6, v2
	v_and_b32_e32 v3, -16, v3
	s_add_u32 s10, s3, s2
	v_readlane_b32 s2, v251, 51
	v_add_u32_e32 v3, v9, v3
	s_addc_u32 s11, s2, 0
	v_and_b32_e32 v4, 3, v9
	s_mov_b32 s2, 0x1fffe0
	v_lshrrev_b32_e32 v5, 2, v3
	v_lshlrev_b32_e32 v6, 1, v3
	v_and_b32_e32 v2, 0xc0, v2
	v_and_or_b32 v4, v3, s2, v4
	v_and_b32_e32 v5, 4, v5
	v_and_b32_e32 v6, 24, v6
	v_sub_u32_e32 v1, v1, v2
	v_or3_b32 v4, v4, v5, v6
	v_lshlrev_b32_e32 v5, 5, v8
	v_ashrrev_i16_sdwa v1, v223, sext(v1) dst_sel:DWORD dst_unused:UNUSED_PAD src0_sel:DWORD src1_sel:BYTE_0
	v_and_b32_e32 v5, 32, v5
	v_bfe_i32 v10, v1, 0, 16
	v_add_lshl_u32 v1, v5, v10, 1
	v_mov_b32_e32 v144, v247
	v_mov_b32_e32 v146, v245
	v_bfe_i32 v1, v184, 27, 1
	v_lshrrev_b32_e32 v1, 22, v1
	v_add_u32_e32 v1, v0, v1
	v_and_b32_e32 v1, 0xfffffc00, v1
	v_sub_u32_e32 v0, v0, v1
	v_lshrrev_b32_e32 v1, 4, v0
	v_ashrrev_i32_e32 v2, 31, v184
	v_bitop3_b32 v0, v1, v0, 32 bitop3:0x6c
	v_lshrrev_b32_e32 v2, 26, v2
	v_ashrrev_i32_e32 v1, 31, v0
	v_add_u32_e32 v2, v184, v2
	v_lshrrev_b32_e32 v1, 26, v1
	v_ashrrev_i32_e32 v12, 6, v2
	v_add_u32_e32 v1, v0, v1
	v_lshlrev_b32_e32 v2, 3, v12
	v_ashrrev_i32_e32 v11, 6, v1
	v_and_b32_e32 v2, -16, v2
	s_ashr_i32 s18, s4, 6
	v_add_u32_e32 v2, v11, v2
	v_and_b32_e32 v3, 3, v11
	s_ashr_i32 s5, s4, 8
	s_lshl_b32 s12, s18, 10
	v_and_or_b32 v3, v2, s2, v3
	v_lshrrev_b32_e32 v4, 2, v2
	v_lshlrev_b32_e32 v5, 1, v2
	v_and_b32_e32 v1, 0xc0, v1
	v_readlane_b32 s2, v253, 53
	v_and_b32_e32 v4, 4, v4
	v_and_b32_e32 v5, 24, v5
	v_sub_u32_e32 v0, v0, v1
	v_readlane_b32 s3, v253, 54
	s_add_u32 s2, s10, s2
	v_or3_b32 v3, v3, v4, v5
	v_lshlrev_b32_e32 v4, 5, v12
	v_ashrrev_i16_sdwa v0, v223, sext(v0) dst_sel:DWORD dst_unused:UNUSED_PAD src0_sel:DWORD src1_sel:BYTE_0
	s_addc_u32 s3, s11, s3
	v_readlane_b32 s6, v251, 21
	v_and_b32_e32 v4, 32, v4
	v_bfe_i32 v13, v0, 0, 16
	s_add_u32 s24, s2, s6
	v_readlane_b32 s2, v251, 20
	v_add_lshl_u32 v0, v4, v13, 1
	s_addc_u32 s25, s3, s2
	s_add_i32 s14, s12, 0
	v_mov_b32_e32 v168, v246
	s_add_i32 m0, s14, 0x10000
	v_readlane_b32 s20, v251, 16
	global_load_lds_dwordx4 v168, s[24:25]
	s_add_i32 m0, s14, 0x12000
	s_add_u32 s2, s24, 0x40000
	global_load_lds_dwordx4 v144, s[24:25]
	s_addc_u32 s3, s25, 0
	s_add_i32 m0, s14, 0x14000
	v_readlane_b32 s21, v251, 17
	global_load_lds_dwordx4 v168, s[2:3]
	s_add_i32 m0, s14, 0x16000
	v_mov_b32_e32 v148, v244
	global_load_lds_dwordx4 v144, s[2:3]
	v_readlane_b32 s2, v253, 63
	v_readlane_b32 s3, v251, 0
	s_add_u32 s26, s20, s2
	s_addc_u32 s27, s21, s3
	s_add_i32 s15, s14, 0x2000
	s_mov_b32 m0, s14
	s_add_u32 s2, s26, 0x40000
	global_load_lds_dwordx4 v148, s[26:27]
	s_mov_b32 m0, s15
	s_addc_u32 s3, s27, 0
	s_add_i32 s16, s14, 0x4000
	global_load_lds_dwordx4 v146, s[26:27]
	s_mov_b32 m0, s16
	s_add_i32 s17, s14, 0x6000
	global_load_lds_dwordx4 v148, s[2:3]
	s_mov_b32 m0, s17
	v_mov_b32_e32 v145, v169
	global_load_lds_dwordx4 v146, s[2:3]
	v_mov_b32_e32 v149, v169
	v_mov_b32_e32 v147, v169
	s_cmp_eq_u32 s5, 1
	s_mov_b64 s[54:55], s[28:29]
	v_lshl_add_u64 v[6:7], s[24:25], 0, v[168:169]
	v_lshl_add_u64 v[4:5], s[24:25], 0, v[144:145]
	v_lshl_add_u64 v[0:1], s[26:27], 0, v[148:149]
	s_cselect_b64 s[2:3], -1, 0
	s_cmp_lg_u32 s5, 1
	v_lshl_add_u64 v[2:3], s[26:27], 0, v[146:147]
	v_readlane_b32 s22, v251, 18
	v_readlane_b32 s23, v251, 19
	s_cbranch_scc1 .LBB0_418
	s_barrier

; #define PG8_STAGE(bufoff, gbase, voff) do { _Pragma("unroll") for (int _i = 0; _i < 2; ++_i) \
;         __builtin_amdgcn_global_load_lds((const unsigned*)((const char*)(gbase) + (voff)[_i]), (PG8_LAS unsigned*)(lds + (bufoff) + ldsw + _i * 8192), 16, 0, 0); } while (0)
; #define PG8_LDA(dst, b, h) do { _Pragma("unroll") for (int m = 0; m < 4; ++m) _Pragma("unroll") for (int k = 0; k < 2; ++k) dst[m][k] = *(const PG8_LAS bf16x8*)(lds + PG8_SA(b, h) + aoff + m * 2048 + k * 1024); } while (0)
; #define PG8_LDB(dst, b, h) do { _Pragma("unroll") for (int n = 0; n < 2; ++n) _Pragma("unroll") for (int k = 0; k < 2; ++k) dst[n][k] = *(const PG8_LAS bf16x8*)(lds + PG8_SB(b, h) + boff + n * 2048 + k * 1024); } while (0)
; #define PG8_MMA(ai, bj, At, Bt) do { __builtin_amdgcn_s_setprio(1); _Pragma("unroll") for (int m = 0; m < 4; ++m) _Pragma("unroll") for (int n = 0; n < 2; ++n) _Pragma("unroll") for (int k = 0; k < 2; ++k) \
;         acc[ai][bj][m][n] = __builtin_amdgcn_mfma_f32_16x16x32_bf16(Bt[n][k], At[m][k], acc[ai][bj][m][n], 0, 0, 0); __builtin_amdgcn_s_setprio(0); } while (0)
; #define PG8_WAIT_V(n) asm volatile("s_waitcnt vmcnt(" #n ")" ::: "memory")
; #define PG8_BAR __builtin_amdgcn_s_barrier()
; template <class Epi, class Sched, bool ALIGN_EPI = false, bool SP2 = false>
; __device__ __forceinline__ void gemm_phase(PG8_LAS unsigned char* lds, const int tid, const Gemm g, const Sched& S, const Epi& E) {
;     ...
;     for (;;) {
;         const bool has_next = S.next(ui + 1, nxt);
;         const char* nA = has_next ? (const char*)g.A + (size_t)nxt.pm * tstep : cA; const char* nB = has_next ? (const char*)g.Bt + (size_t)nxt.pn * tstep + (size_t)(nxt.pm >> 5) * g.bstride : cB;
;         for (int t = 0; t < nt; t += 2) {
;             const bool last = (t == nt - 2);
;             const char* a1 = cA + (size_t)(t + 1) * kstep;
;             const char* a2 = last ? nA : cA + (size_t)(t + 2) * kstep; const char* b2 = last ? nB : cB + (size_t)(t + 2) * kstep;
;             const char* a3 = a2 + kstep; const char* b3 = b2 + kstep;
;             if (last && has_next) S.a_ready(nxt);
;             if constexpr (SP2) {
;             PG8_LDB(B0, 0, 0); PG8_LDB(B1, 0, 1); PG8_SCHED; PG8_LDA(At, 0, 0); PG8_STAGE(PG8_SA(1, 1), a1 + hstep, voffA);
;             PG8_WAIT_V(8); PG8_WAIT_L(0); PG8_BAR; PG8_MMA(0, 0, At, B0); PG8_MMA(0, 1, At, B1); PG8_BAR; PG8_SCHED;
.LBB0_425:
	s_ashr_i32 s41, s40, 31
	s_lshl_b64 s[44:45], s[40:41], 19
	v_readlane_b32 s48, v251, 16
	v_readlane_b32 s49, v251, 17
	s_add_u32 s44, s48, s44
	s_addc_u32 s45, s49, s45
	s_and_b64 s[4:5], s[4:5], exec
	s_cselect_b32 s39, s45, s27
	s_cselect_b32 s41, s44, s26
	s_add_u32 s4, s26, 0x40080
	s_addc_u32 s5, s27, 0
	s_add_u32 s46, s24, 0x100
	s_addc_u32 s47, s25, 0
	s_mov_b32 s48, -2
	v_readlane_b32 s50, v251, 18
	v_readlane_b32 s51, v251, 19
	s_and_b32 s90, s20, 1
	s_lshl_b32 s90, s90, 11
	s_add_i32 s90, s90, 0x20000
	s_ashr_i32 s92, s23, 5
	s_mul_hi_i32 s93, s92, 0x5800
	s_mul_i32 s92, s92, 0x5800
	s_add_u32 s92, s8, s92
	s_addc_u32 s93, s9, s93
	s_lshl_b32 s94, s22, 10
	s_add_u32 s92, s92, s94
	s_addc_u32 s93, s93, 0
	s_mov_b32 m0, s90
	s_nop 0
	global_load_lds_dwordx4 v234, s[92:93]
	s_lshl_b32 s94, s23, 10
	s_add_u32 s92, s6, s94
	s_addc_u32 s93, s7, 0
	s_add_i32 m0, s90, 0x400
	s_nop 0
	global_load_lds_dwordx4 v234, s[92:93]
	s_add_u32 s24, s4, 0xfffc0080
	s_addc_u32 s25, s5, -1
	s_cmp_eq_u32 s48, 12
	s_cselect_b32 s27, s39, s25
	s_cselect_b32 s26, s41, s24
	s_cselect_b32 s25, s43, s47
	s_cselect_b32 s24, s42, s46
	ds_read_b128 v[64:67], v244
	ds_read_b128 v[68:71], v245
	ds_read_b128 v[72:75], v244 offset:2048
	ds_read_b128 v[76:79], v245 offset:2048
	ds_read_b128 v[154:157], v244 offset:16384
	ds_read_b128 v[164:167], v245 offset:16384
	ds_read_b128 v[186:189], v244 offset:18432
	ds_read_b128 v[190:193], v245 offset:18432
	s_add_i32 m0, s14, 0xc000
	ds_read_b128 v[194:197], v161
	ds_read_b128 v[198:201], v249
	ds_read_b128 v[202:205], v161 offset:2048
	ds_read_b128 v[206:209], v249 offset:2048
	ds_read_b128 v[210:213], v161 offset:4096
	ds_read_b128 v[214:217], v249 offset:4096
	ds_read_b128 v[218:221], v161 offset:6144
	ds_read_b128 v[230:233], v249 offset:6144
	global_load_lds_dwordx4 v150, s[4:5]
	s_add_i32 m0, s14, 0xe000
	s_nop 0
	global_load_lds_dwordx4 v152, s[4:5]
	s_waitcnt vmcnt(8)
	s_waitcnt lgkmcnt(0)
	s_barrier
	s_setprio 1
	s_waitcnt lgkmcnt(0)
	v_mfma_f32_16x16x32_bf16 v[140:143], v[64:67], v[194:197], 0
	v_mfma_f32_16x16x32_bf16 v[136:139], v[72:75], v[194:197], 0
	v_mfma_f32_16x16x32_bf16 v[124:127], v[64:67], v[202:205], 0
	v_mfma_f32_16x16x32_bf16 v[120:123], v[72:75], v[202:205], 0
	v_mfma_f32_16x16x32_bf16 v[108:111], v[64:67], v[210:213], 0
	v_mfma_f32_16x16x32_bf16 v[104:107], v[72:75], v[210:213], 0
	v_mfma_f32_16x16x32_bf16 v[92:95], v[64:67], v[218:221], 0
	v_mfma_f32_16x16x32_bf16 v[88:91], v[72:75], v[218:221], 0
	v_mfma_f32_16x16x32_bf16 v[140:143], v[68:71], v[198:201], v[140:143]
	v_mfma_f32_16x16x32_bf16 v[136:139], v[76:79], v[198:201], v[136:139]
	v_mfma_f32_16x16x32_bf16 v[124:127], v[68:71], v[206:209], v[124:127]
	v_mfma_f32_16x16x32_bf16 v[120:123], v[76:79], v[206:209], v[120:123]
	v_mfma_f32_16x16x32_bf16 v[108:111], v[68:71], v[214:217], v[108:111]
	v_mfma_f32_16x16x32_bf16 v[104:107], v[76:79], v[214:217], v[104:107]
	v_mfma_f32_16x16x32_bf16 v[92:95], v[68:71], v[230:233], v[92:95]
	v_mfma_f32_16x16x32_bf16 v[88:91], v[76:79], v[230:233], v[88:91]
	s_setprio 0
	s_setprio 1
	v_mfma_f32_16x16x32_bf16 v[132:135], v[154:157], v[194:197], 0
	v_mfma_f32_16x16x32_bf16 v[128:131], v[186:189], v[194:197], 0
	v_mfma_f32_16x16x32_bf16 v[116:119], v[154:157], v[202:205], 0
	v_mfma_f32_16x16x32_bf16 v[112:115], v[186:189], v[202:205], 0
	v_mfma_f32_16x16x32_bf16 v[100:103], v[154:157], v[210:213], 0
	v_mfma_f32_16x16x32_bf16 v[96:99], v[186:189], v[210:213], 0
	v_mfma_f32_16x16x32_bf16 v[84:87], v[154:157], v[218:221], 0
	v_mfma_f32_16x16x32_bf16 v[80:83], v[186:189], v[218:221], 0
	v_mfma_f32_16x16x32_bf16 v[132:135], v[164:167], v[198:201], v[132:135]
	v_mfma_f32_16x16x32_bf16 v[128:131], v[190:193], v[198:201], v[128:131]
	v_mfma_f32_16x16x32_bf16 v[116:119], v[164:167], v[206:209], v[116:119]
	v_mfma_f32_16x16x32_bf16 v[112:115], v[190:193], v[206:209], v[112:115]
	v_mfma_f32_16x16x32_bf16 v[100:103], v[164:167], v[214:217], v[100:103]
	v_mfma_f32_16x16x32_bf16 v[96:99], v[190:193], v[214:217], v[96:99]
	v_mfma_f32_16x16x32_bf16 v[84:87], v[164:167], v[230:233], v[84:87]
	v_mfma_f32_16x16x32_bf16 v[80:83], v[190:193], v[230:233], v[80:83]
	s_setprio 0
	s_barrier
	s_add_i32 m0, s12, 0x10000
	ds_read_b128 v[194:197], v161 offset:16384
	ds_read_b128 v[198:201], v249 offset:16384
	ds_read_b128 v[202:205], v161 offset:18432
	ds_read_b128 v[206:209], v249 offset:18432
	ds_read_b128 v[210:213], v161 offset:20480
	ds_read_b128 v[214:217], v249 offset:20480
	ds_read_b128 v[218:221], v161 offset:22528
	ds_read_b128 v[230:233], v249 offset:22528
	global_load_lds_dwordx4 v168, s[24:25]
	s_add_i32 m0, s12, 0x12000
	s_add_u32 s50, s24, 0x40000
	s_addc_u32 s51, s25, 0
	global_load_lds_dwordx4 v144, s[24:25]
	s_add_i32 m0, s12, 0x14000
	s_nop 0
	global_load_lds_dwordx4 v168, s[50:51]
	s_add_i32 m0, s12, 0x16000
	s_nop 0
	global_load_lds_dwordx4 v144, s[50:51]
	s_mov_b32 m0, s14
	s_nop 0
	global_load_lds_dwordx4 v148, s[26:27]
	s_mov_b32 m0, s15
	s_nop 0
	global_load_lds_dwordx4 v146, s[26:27]
	s_waitcnt vmcnt(8)
	s_waitcnt lgkmcnt(0)
	s_barrier
; #define PG8_STAGE(bufoff, gbase, voff) do { _Pragma("unroll") for (int _i = 0; _i < 2; ++_i) \
;         __builtin_amdgcn_global_load_lds((const unsigned*)((const char*)(gbase) + (voff)[_i]), (PG8_LAS unsigned*)(lds + (bufoff) + ldsw + _i * 8192), 16, 0, 0); } while (0)
; #define PG8_LDA(dst, b, h) do { _Pragma("unroll") for (int m = 0; m < 4; ++m) _Pragma("unroll") for (int k = 0; k < 2; ++k) dst[m][k] = *(const PG8_LAS bf16x8*)(lds + PG8_SA(b, h) + aoff + m * 2048 + k * 1024); } while (0)
; #define PG8_LDB(dst, b, h) do { _Pragma("unroll") for (int n = 0; n < 2; ++n) _Pragma("unroll") for (int k = 0; k < 2; ++k) dst[n][k] = *(const PG8_LAS bf16x8*)(lds + PG8_SB(b, h) + boff + n * 2048 + k * 1024); } while (0)
; #define PG8_MMA(ai, bj, At, Bt) do { __builtin_amdgcn_s_setprio(1); _Pragma("unroll") for (int m = 0; m < 4; ++m) _Pragma("unroll") for (int n = 0; n < 2; ++n) _Pragma("unroll") for (int k = 0; k < 2; ++k) \
;         acc[ai][bj][m][n] = __builtin_amdgcn_mfma_f32_16x16x32_bf16(Bt[n][k], At[m][k], acc[ai][bj][m][n], 0, 0, 0); __builtin_amdgcn_s_setprio(0); } while (0)
; #define PG8_WAIT_V(n) asm volatile("s_waitcnt vmcnt(" #n ")" ::: "memory")
; #define PG8_WAIT_L(n) asm volatile("s_waitcnt lgkmcnt(" #n ")" ::: "memory")
; #define PG8_BAR __builtin_amdgcn_s_barrier()
; #define PG8_SCHED __builtin_amdgcn_sched_barrier(0)
; template <class Epi, class Sched, bool ALIGN_EPI = false, bool SP2 = false>
; __device__ __forceinline__ void gemm_phase(PG8_LAS unsigned char* lds, const int tid, const Gemm g, const Sched& S, const Epi& E) {
;     ...
;             PG8_WAIT_V(8); PG8_WAIT_L(0); PG8_BAR; PG8_MMA(0, 0, At, B0); PG8_MMA(0, 1, At, B1); PG8_BAR; PG8_SCHED;
;             PG8_LDA(At, 0, 1); PG8_STAGE(PG8_SB(0, 0), b2, voffB); PG8_STAGE(PG8_SB(0, 1), b2 + hstep, voffB); PG8_STAGE(PG8_SA(0, 0), a2, voffA);
;             PG8_WAIT_V(8); PG8_WAIT_L(0); PG8_BAR; PG8_MMA(1, 0, At, B0); PG8_MMA(1, 1, At, B1); PG8_BAR; PG8_SCHED;
;             PG8_LDB(B0, 1, 0); PG8_LDB(B1, 1, 1); PG8_SCHED; PG8_LDA(At, 1, 0); PG8_STAGE(PG8_SA(0, 1), a2 + hstep, voffA);
;             PG8_WAIT_V(8); PG8_WAIT_L(0); PG8_BAR; PG8_MMA(0, 0, At, B0); PG8_MMA(0, 1, At, B1); PG8_BAR; PG8_SCHED;
	s_setprio 1
	s_waitcnt lgkmcnt(0)
	v_mfma_f32_16x16x32_bf16 v[60:63], v[64:67], v[194:197], 0
	v_mfma_f32_16x16x32_bf16 v[56:59], v[72:75], v[194:197], 0
	v_mfma_f32_16x16x32_bf16 v[44:47], v[64:67], v[202:205], 0
	v_mfma_f32_16x16x32_bf16 v[40:43], v[72:75], v[202:205], 0
	v_mfma_f32_16x16x32_bf16 v[28:31], v[64:67], v[210:213], 0
	v_mfma_f32_16x16x32_bf16 v[24:27], v[72:75], v[210:213], 0
	v_mfma_f32_16x16x32_bf16 v[12:15], v[64:67], v[218:221], 0
	v_mfma_f32_16x16x32_bf16 v[8:11], v[72:75], v[218:221], 0
	v_mfma_f32_16x16x32_bf16 v[60:63], v[68:71], v[198:201], v[60:63]
	v_mfma_f32_16x16x32_bf16 v[56:59], v[76:79], v[198:201], v[56:59]
	v_mfma_f32_16x16x32_bf16 v[44:47], v[68:71], v[206:209], v[44:47]
	v_mfma_f32_16x16x32_bf16 v[40:43], v[76:79], v[206:209], v[40:43]
	v_mfma_f32_16x16x32_bf16 v[28:31], v[68:71], v[214:217], v[28:31]
	v_mfma_f32_16x16x32_bf16 v[24:27], v[76:79], v[214:217], v[24:27]
	v_mfma_f32_16x16x32_bf16 v[12:15], v[68:71], v[230:233], v[12:15]
	v_mfma_f32_16x16x32_bf16 v[8:11], v[76:79], v[230:233], v[8:11]
	s_setprio 0
	s_setprio 1
	v_mfma_f32_16x16x32_bf16 v[52:55], v[154:157], v[194:197], 0
	v_mfma_f32_16x16x32_bf16 v[48:51], v[186:189], v[194:197], 0
	v_mfma_f32_16x16x32_bf16 v[36:39], v[154:157], v[202:205], 0
	v_mfma_f32_16x16x32_bf16 v[32:35], v[186:189], v[202:205], 0
	v_mfma_f32_16x16x32_bf16 v[20:23], v[154:157], v[210:213], 0
	v_mfma_f32_16x16x32_bf16 v[16:19], v[186:189], v[210:213], 0
	v_mfma_f32_16x16x32_bf16 v[4:7], v[154:157], v[218:221], 0
	v_mfma_f32_16x16x32_bf16 v[0:3], v[186:189], v[218:221], 0
	v_mfma_f32_16x16x32_bf16 v[52:55], v[164:167], v[198:201], v[52:55]
	v_mfma_f32_16x16x32_bf16 v[48:51], v[190:193], v[198:201], v[48:51]
	v_mfma_f32_16x16x32_bf16 v[36:39], v[164:167], v[206:209], v[36:39]
	v_mfma_f32_16x16x32_bf16 v[32:35], v[190:193], v[206:209], v[32:35]
	v_mfma_f32_16x16x32_bf16 v[20:23], v[164:167], v[214:217], v[20:23]
	v_mfma_f32_16x16x32_bf16 v[16:19], v[190:193], v[214:217], v[16:19]
	v_mfma_f32_16x16x32_bf16 v[4:7], v[164:167], v[230:233], v[4:7]
	v_mfma_f32_16x16x32_bf16 v[0:3], v[190:193], v[230:233], v[0:3]
	s_setprio 0
	s_barrier
	ds_read_b128 v[64:67], v244 offset:32768
	ds_read_b128 v[68:71], v245 offset:32768
	ds_read_b128 v[72:75], v244 offset:34816
	ds_read_b128 v[76:79], v245 offset:34816
	ds_read_b128 v[154:157], v244 offset:49152
	ds_read_b128 v[164:167], v245 offset:49152
	ds_read_b128 v[186:189], v244 offset:51200
	ds_read_b128 v[190:193], v245 offset:51200
	s_add_u32 s26, s26, 0x40000
	s_addc_u32 s27, s27, 0
	s_mov_b32 m0, s16
	ds_read_b128 v[194:197], v161 offset:32768
	ds_read_b128 v[198:201], v249 offset:32768
	ds_read_b128 v[202:205], v161 offset:34816
	ds_read_b128 v[206:209], v249 offset:34816
	ds_read_b128 v[210:213], v161 offset:36864
	ds_read_b128 v[214:217], v249 offset:36864
	ds_read_b128 v[218:221], v161 offset:38912
	ds_read_b128 v[230:233], v249 offset:38912
	global_load_lds_dwordx4 v148, s[26:27]
	s_mov_b32 m0, s17
	s_nop 0
	global_load_lds_dwordx4 v146, s[26:27]
	s_waitcnt vmcnt(8)
	s_waitcnt lgkmcnt(0)
	s_barrier
	s_setprio 1
	s_waitcnt lgkmcnt(0)
	v_mfma_f32_16x16x32_bf16 v[140:143], v[64:67], v[194:197], v[140:143]
	v_mfma_f32_16x16x32_bf16 v[136:139], v[72:75], v[194:197], v[136:139]
	v_mfma_f32_16x16x32_bf16 v[124:127], v[64:67], v[202:205], v[124:127]
	v_mfma_f32_16x16x32_bf16 v[120:123], v[72:75], v[202:205], v[120:123]
	v_mfma_f32_16x16x32_bf16 v[108:111], v[64:67], v[210:213], v[108:111]
	v_mfma_f32_16x16x32_bf16 v[104:107], v[72:75], v[210:213], v[104:107]
	v_mfma_f32_16x16x32_bf16 v[92:95], v[64:67], v[218:221], v[92:95]
	v_mfma_f32_16x16x32_bf16 v[88:91], v[72:75], v[218:221], v[88:91]
	v_mfma_f32_16x16x32_bf16 v[140:143], v[68:71], v[198:201], v[140:143]
	v_mfma_f32_16x16x32_bf16 v[136:139], v[76:79], v[198:201], v[136:139]
	v_mfma_f32_16x16x32_bf16 v[124:127], v[68:71], v[206:209], v[124:127]
	v_mfma_f32_16x16x32_bf16 v[120:123], v[76:79], v[206:209], v[120:123]
	v_mfma_f32_16x16x32_bf16 v[108:111], v[68:71], v[214:217], v[108:111]
	v_mfma_f32_16x16x32_bf16 v[104:107], v[76:79], v[214:217], v[104:107]
	v_mfma_f32_16x16x32_bf16 v[92:95], v[68:71], v[230:233], v[92:95]
	v_mfma_f32_16x16x32_bf16 v[88:91], v[76:79], v[230:233], v[88:91]
	s_setprio 0
	s_setprio 1
	v_mfma_f32_16x16x32_bf16 v[132:135], v[154:157], v[194:197], v[132:135]
	v_mfma_f32_16x16x32_bf16 v[128:131], v[186:189], v[194:197], v[128:131]
	v_mfma_f32_16x16x32_bf16 v[116:119], v[154:157], v[202:205], v[116:119]
	v_mfma_f32_16x16x32_bf16 v[112:115], v[186:189], v[202:205], v[112:115]
	v_mfma_f32_16x16x32_bf16 v[100:103], v[154:157], v[210:213], v[100:103]
	v_mfma_f32_16x16x32_bf16 v[96:99], v[186:189], v[210:213], v[96:99]
	v_mfma_f32_16x16x32_bf16 v[84:87], v[154:157], v[218:221], v[84:87]
	v_mfma_f32_16x16x32_bf16 v[80:83], v[186:189], v[218:221], v[80:83]
	v_mfma_f32_16x16x32_bf16 v[132:135], v[164:167], v[198:201], v[132:135]
	v_mfma_f32_16x16x32_bf16 v[128:131], v[190:193], v[198:201], v[128:131]
	v_mfma_f32_16x16x32_bf16 v[116:119], v[164:167], v[206:209], v[116:119]
	v_mfma_f32_16x16x32_bf16 v[112:115], v[190:193], v[206:209], v[112:115]
	v_mfma_f32_16x16x32_bf16 v[100:103], v[164:167], v[214:217], v[100:103]
	v_mfma_f32_16x16x32_bf16 v[96:99], v[190:193], v[214:217], v[96:99]
	v_mfma_f32_16x16x32_bf16 v[84:87], v[164:167], v[230:233], v[84:87]
	v_mfma_f32_16x16x32_bf16 v[80:83], v[190:193], v[230:233], v[80:83]
	s_setprio 0
	s_barrier
; #define PG8_STAGE(bufoff, gbase, voff) do { _Pragma("unroll") for (int _i = 0; _i < 2; ++_i) \
;         __builtin_amdgcn_global_load_lds((const unsigned*)((const char*)(gbase) + (voff)[_i]), (PG8_LAS unsigned*)(lds + (bufoff) + ldsw + _i * 8192), 16, 0, 0); } while (0)
; #define PG8_LDA(dst, b, h) do { _Pragma("unroll") for (int m = 0; m < 4; ++m) _Pragma("unroll") for (int k = 0; k < 2; ++k) dst[m][k] = *(const PG8_LAS bf16x8*)(lds + PG8_SA(b, h) + aoff + m * 2048 + k * 1024); } while (0)
; #define PG8_MMA(ai, bj, At, Bt) do { __builtin_amdgcn_s_setprio(1); _Pragma("unroll") for (int m = 0; m < 4; ++m) _Pragma("unroll") for (int n = 0; n < 2; ++n) _Pragma("unroll") for (int k = 0; k < 2; ++k) \
;         acc[ai][bj][m][n] = __builtin_amdgcn_mfma_f32_16x16x32_bf16(Bt[n][k], At[m][k], acc[ai][bj][m][n], 0, 0, 0); __builtin_amdgcn_s_setprio(0); } while (0)
; #define PG8_WAIT_V(n) asm volatile("s_waitcnt vmcnt(" #n ")" ::: "memory")
; #define PG8_WAIT_L(n) asm volatile("s_waitcnt lgkmcnt(" #n ")" ::: "memory")
; #define PG8_BAR __builtin_amdgcn_s_barrier()
; #define PG8_SCHED __builtin_amdgcn_sched_barrier(0)
; template <class Epi, class Sched, bool ALIGN_EPI = false, bool SP2 = false>
; __device__ __forceinline__ void gemm_phase(PG8_LAS unsigned char* lds, const int tid, const Gemm g, const Sched& S, const Epi& E) {
;     ...
;             PG8_LDA(At, 1, 1); PG8_STAGE(PG8_SB(1, 0), b3, voffB); PG8_STAGE(PG8_SB(1, 1), b3 + hstep, voffB); PG8_STAGE(PG8_SA(1, 0), a3, voffA);
;             PG8_WAIT_V(8); PG8_WAIT_L(0); PG8_BAR; PG8_MMA(1, 0, At, B0); PG8_MMA(1, 1, At, B1); PG8_BAR; PG8_SCHED;
	s_add_u32 s94, s24, 0x80
	s_addc_u32 s95, s25, 0
	s_add_i32 m0, s12, 0x18000
	ds_read_b128 v[194:197], v161 offset:49152
	ds_read_b128 v[198:201], v249 offset:49152
	ds_read_b128 v[202:205], v161 offset:51200
	ds_read_b128 v[206:209], v249 offset:51200
	ds_read_b128 v[210:213], v161 offset:53248
	ds_read_b128 v[214:217], v249 offset:53248
	ds_read_b128 v[218:221], v161 offset:55296
	ds_read_b128 v[230:233], v249 offset:55296
	global_load_lds_dwordx4 v168, s[94:95]
	s_add_i32 m0, s12, 0x1a000
	s_add_u32 s24, s24, 0x40080
	s_addc_u32 s25, s25, 0
	global_load_lds_dwordx4 v144, s[94:95]
	s_add_i32 m0, s12, 0x1c000
	s_add_u32 s92, s26, 0xfffc0080
	s_addc_u32 s93, s27, -1
	global_load_lds_dwordx4 v168, s[24:25]
	s_add_i32 m0, s12, 0x1e000
	s_nop 0
	global_load_lds_dwordx4 v144, s[24:25]
	s_mov_b32 m0, s18
	s_nop 0
	global_load_lds_dwordx4 v148, s[92:93]
	s_mov_b32 m0, s19
	s_nop 0
	global_load_lds_dwordx4 v146, s[92:93]
	s_waitcnt vmcnt(8)
	s_waitcnt lgkmcnt(0)
	s_barrier
	s_setprio 1
	s_waitcnt lgkmcnt(0)
	v_mfma_f32_16x16x32_bf16 v[60:63], v[64:67], v[194:197], v[60:63]
	v_mfma_f32_16x16x32_bf16 v[56:59], v[72:75], v[194:197], v[56:59]
	v_mfma_f32_16x16x32_bf16 v[44:47], v[64:67], v[202:205], v[44:47]
	v_mfma_f32_16x16x32_bf16 v[40:43], v[72:75], v[202:205], v[40:43]
	v_mfma_f32_16x16x32_bf16 v[28:31], v[64:67], v[210:213], v[28:31]
	v_mfma_f32_16x16x32_bf16 v[24:27], v[72:75], v[210:213], v[24:27]
	v_mfma_f32_16x16x32_bf16 v[12:15], v[64:67], v[218:221], v[12:15]
	v_mfma_f32_16x16x32_bf16 v[8:11], v[72:75], v[218:221], v[8:11]
	v_mfma_f32_16x16x32_bf16 v[60:63], v[68:71], v[198:201], v[60:63]
	v_mfma_f32_16x16x32_bf16 v[56:59], v[76:79], v[198:201], v[56:59]
	v_mfma_f32_16x16x32_bf16 v[44:47], v[68:71], v[206:209], v[44:47]
	v_mfma_f32_16x16x32_bf16 v[40:43], v[76:79], v[206:209], v[40:43]
	v_mfma_f32_16x16x32_bf16 v[28:31], v[68:71], v[214:217], v[28:31]
	v_mfma_f32_16x16x32_bf16 v[24:27], v[76:79], v[214:217], v[24:27]
	v_mfma_f32_16x16x32_bf16 v[12:15], v[68:71], v[230:233], v[12:15]
	v_mfma_f32_16x16x32_bf16 v[8:11], v[76:79], v[230:233], v[8:11]
	s_setprio 0
	s_setprio 1
	v_mfma_f32_16x16x32_bf16 v[52:55], v[154:157], v[194:197], v[52:55]
	v_mfma_f32_16x16x32_bf16 v[48:51], v[186:189], v[194:197], v[48:51]
	v_mfma_f32_16x16x32_bf16 v[36:39], v[154:157], v[202:205], v[36:39]
	v_mfma_f32_16x16x32_bf16 v[32:35], v[186:189], v[202:205], v[32:35]
	v_mfma_f32_16x16x32_bf16 v[20:23], v[154:157], v[210:213], v[20:23]
	v_mfma_f32_16x16x32_bf16 v[16:19], v[186:189], v[210:213], v[16:19]
	v_mfma_f32_16x16x32_bf16 v[4:7], v[154:157], v[218:221], v[4:7]
	v_mfma_f32_16x16x32_bf16 v[0:3], v[186:189], v[218:221], v[0:3]
	v_mfma_f32_16x16x32_bf16 v[52:55], v[164:167], v[198:201], v[52:55]
	v_mfma_f32_16x16x32_bf16 v[48:51], v[190:193], v[198:201], v[48:51]
	v_mfma_f32_16x16x32_bf16 v[36:39], v[164:167], v[206:209], v[36:39]
	v_mfma_f32_16x16x32_bf16 v[32:35], v[190:193], v[206:209], v[32:35]
	v_mfma_f32_16x16x32_bf16 v[20:23], v[164:167], v[214:217], v[20:23]
	v_mfma_f32_16x16x32_bf16 v[16:19], v[190:193], v[214:217], v[16:19]
	v_mfma_f32_16x16x32_bf16 v[4:7], v[164:167], v[230:233], v[4:7]
	v_mfma_f32_16x16x32_bf16 v[0:3], v[190:193], v[230:233], v[0:3]
	s_setprio 0
	s_barrier
	s_add_i32 s48, s48, 2
	s_add_u32 s4, s4, 0x100
	s_addc_u32 s5, s5, 0
	s_add_u32 s46, s46, 0x100
	s_addc_u32 s47, s47, 0
	s_cmp_gt_u32 s48, 13
	s_cbranch_scc0 .LBB0_426
	s_branch .Lpeel_exit_g3

; __device__ __forceinline__ float silu_f(float g) { return g * __builtin_amdgcn_rcpf(1.0f + __builtin_amdgcn_exp2f(-1.4426950408889634f * g)); }
;     __device__ __forceinline__ void operator()(const f32x4 (&acc)[2][2][4][2], const Unit& u, int wr, int wc, int fr, int fq) const {
;         const int row0 = u.pm * BM + wr * 64 + fr, col0 = u.pn * HALF + wc * 32 + 8 * fq;
;         const float* swp = sw + (size_t)((u.pm * BM) >> 13) * (2 * 2816) + u.pn * BM + wc * 32 + 8 * fq;
;         f32x4 sv[2][2];
; #pragma unroll
;         for (int bj = 0; bj < 2; ++bj)
; #pragma unroll
;             for (int n = 0; n < 2; ++n) sv[bj][n] = *(const f32x4*)(swp + bj * HALF + 4 * n);
;         float rsv[2][4];
; #pragma unroll
;         for (int ai = 0; ai < 2; ++ai)
; #pragma unroll
;             for (int m = 0; m < 4; ++m) rsv[ai][m] = rss[row0 + ai * HALF + m * 16];
; #pragma unroll
;         for (int ai = 0; ai < 2; ++ai)
; #pragma unroll
;             for (int m = 0; m < 4; ++m) {
;                 const float rs = __builtin_amdgcn_rsqf(rsv[ai][m] * (1.0f / 1024.0f) + 1e-6f);
;                 const f32x4 g0 = acc[ai][0][m][0] * rs + sv[0][0], g1 = acc[ai][0][m][1] * rs + sv[0][1], u0 = acc[ai][1][m][0] * rs + sv[1][0], u1 = acc[ai][1][m][1] * rs + sv[1][1];
;                 u32x4 w;
;                 w.x = cvt_pk_bf16(silu_f(g0[0]) * u0[0], silu_f(g0[1]) * u0[1]); w.y = cvt_pk_bf16(silu_f(g0[2]) * u0[2], silu_f(g0[3]) * u0[3]);
;                 w.z = cvt_pk_bf16(silu_f(g1[0]) * u1[0], silu_f(g1[1]) * u1[1]); w.w = cvt_pk_bf16(silu_f(g1[2]) * u1[2], silu_f(g1[3]) * u1[3]);
;                 __builtin_nontemporal_store(w, (u32x4*)(O + (size_t)(row0 + ai * HALF + m * 16) * ldc + col0));
.LBB0_429:
	s_ashr_i32 s4, s23, 5
	s_mul_hi_i32 s5, s4, 0x5800
	s_mulk_i32 s4, 0x5800
	v_lshl_add_u32 v154, s23, 8, v158
	s_add_u32 s23, s8, s4
	s_addc_u32 s24, s9, s5
	s_lshl_b32 s4, s22, 8
	s_ashr_i32 s5, s4, 31
	s_lshl_b64 s[4:5], s[4:5], 2
	s_add_u32 s4, s23, s4
	s_addc_u32 s5, s24, s5
	s_add_u32 s4, s4, s21
	v_ashrrev_i32_e32 v155, 31, v154
	s_addc_u32 s5, s5, 0
	v_lshl_add_u64 v[156:157], v[154:155], 2, s[6:7]
	s_and_b32 s90, s20, 1
	s_lshl_b32 s90, s90, 11
	s_add_i32 s90, s90, 0x20000
	v_add_u32_e32 v235, s21, v162
	v_add_u32_e32 v235, s90, v235
	v_lshl_add_u32 v236, v158, 2, s90
	ds_read_b128 v[72:75], v235 offset:16
	ds_read_b128 v[76:79], v235
	ds_read_b128 v[64:67], v235 offset:528
	ds_read_b128 v[68:71], v235 offset:512
	ds_read_b32 v191, v236 offset:1024
	ds_read_b32 v193, v236 offset:1088
	ds_read_b32 v189, v236 offset:1152
	ds_read_b32 v187, v236 offset:1216
	ds_read_b32 v185, v236 offset:1536
	ds_read_b32 v167, v236 offset:1600
	ds_read_b32 v165, v236 offset:1664
	ds_read_b32 v163, v236 offset:1728
	v_lshl_or_b32 v156, s22, 7, v160
	v_ashrrev_i32_e32 v157, 31, v156
	v_or_b32_e32 v190, 16, v154
	v_or_b32_e32 v188, 32, v154
	v_or_b32_e32 v186, 48, v154
	v_add_u32_e32 v183, 0x80, v154
	v_add_u32_e32 v166, 0x90, v154
	v_add_u32_e32 v164, 0xa0, v154
	v_add_u32_e32 v155, 0xb0, v154
	s_and_b64 vcc, exec, s[0:1]
	s_waitcnt lgkmcnt(0)
	v_fmamk_f32 v191, v191, 0x3a800000, v222
	v_rsq_f32_e32 v192, v191
	s_nop 0
	v_pk_fma_f32 v[140:141], v[140:141], v[192:193], v[76:77] op_sel_hi:[1,0,1]
	v_pk_fma_f32 v[194:195], v[130:131], v[192:193], v[66:67] op_sel_hi:[1,0,1]
	v_pk_fma_f32 v[130:131], v[128:129], v[192:193], v[64:65] op_sel_hi:[1,0,1]
	v_mul_f32_e32 v128, 0xbfb8aa3b, v140
	v_mul_f32_e32 v129, 0xbfb8aa3b, v141
	v_exp_f32_e32 v128, v128
	v_exp_f32_e32 v129, v129
	v_pk_fma_f32 v[132:133], v[132:133], v[192:193], v[68:69] op_sel_hi:[1,0,1]
	v_pk_fma_f32 v[142:143], v[142:143], v[192:193], v[78:79] op_sel_hi:[1,0,1]
	v_add_f32_e32 v128, 1.0, v128
	v_add_f32_e32 v129, 1.0, v129
	v_rcp_f32_e32 v128, v128
	v_rcp_f32_e32 v129, v129
	v_pk_fma_f32 v[134:135], v[134:135], v[192:193], v[70:71] op_sel_hi:[1,0,1]
	v_pk_fma_f32 v[136:137], v[136:137], v[192:193], v[72:73] op_sel_hi:[1,0,1]
	v_pk_fma_f32 v[138:139], v[138:139], v[192:193], v[74:75] op_sel_hi:[1,0,1]
	v_pk_mul_f32 v[128:129], v[140:141], v[128:129]
	s_nop 0
	v_pk_mul_f32 v[128:129], v[132:133], v[128:129]
	s_nop 0
	v_cvt_pk_bf16_f32 v128, v128, v129
	v_mul_f32_e32 v129, 0xbfb8aa3b, v142
	v_exp_f32_e32 v129, v129
	s_nop 0
	v_add_f32_e32 v129, 1.0, v129
	v_rcp_f32_e32 v132, v129
	v_mul_f32_e32 v129, 0xbfb8aa3b, v143
	v_exp_f32_e32 v129, v129
	s_nop 0
	v_add_f32_e32 v129, 1.0, v129
	v_rcp_f32_e32 v133, v129
	s_nop 0
	v_pk_mul_f32 v[132:133], v[142:143], v[132:133]
	s_nop 0
	v_pk_mul_f32 v[132:133], v[134:135], v[132:133]
	v_lshlrev_b64 v[134:135], 1, v[156:157]
	v_cvt_pk_bf16_f32 v129, v132, v133
	v_mul_f32_e32 v132, 0xbfb8aa3b, v136
	v_mul_f32_e32 v133, 0xbfb8aa3b, v137
	v_exp_f32_e32 v132, v132
	v_exp_f32_e32 v133, v133
	v_add_f32_e32 v132, 1.0, v132
	v_add_f32_e32 v133, 1.0, v133
	v_rcp_f32_e32 v132, v132
	v_rcp_f32_e32 v133, v133
	s_nop 0
	v_pk_mul_f32 v[132:133], v[136:137], v[132:133]
	s_nop 0
	v_pk_mul_f32 v[130:131], v[130:131], v[132:133]
	s_nop 0
	v_cvt_pk_bf16_f32 v130, v130, v131
	v_mul_f32_e32 v131, 0xbfb8aa3b, v138
	v_exp_f32_e32 v131, v131
	s_nop 0
	v_add_f32_e32 v131, 1.0, v131
	v_rcp_f32_e32 v132, v131
	v_mul_f32_e32 v131, 0xbfb8aa3b, v139
	v_exp_f32_e32 v131, v131
	s_nop 0
	v_add_f32_e32 v131, 1.0, v131
	v_rcp_f32_e32 v133, v131
	s_nop 0
	v_pk_mul_f32 v[132:133], v[138:139], v[132:133]
	s_nop 0
	v_pk_mul_f32 v[132:133], v[194:195], v[132:133]
	s_nop 0
	v_cvt_pk_bf16_f32 v131, v132, v133
	v_mov_b64_e32 v[132:133], s[54:55]
	v_mad_i64_i32 v[136:137], s[4:5], v154, s31, v[132:133]
	v_lshl_add_u64 v[136:137], v[136:137], 0, v[134:135]
	global_store_dwordx4 v[136:137], v[128:131], off nt
	s_nop 1
	v_fmamk_f32 v128, v193, 0x3a800000, v222
	v_rsq_f32_e32 v128, v128
	s_nop 0
	v_pk_fma_f32 v[124:125], v[124:125], v[128:129], v[76:77] op_sel_hi:[1,0,1]
	v_pk_fma_f32 v[126:127], v[126:127], v[128:129], v[78:79] op_sel_hi:[1,0,1]
	v_pk_fma_f32 v[122:123], v[122:123], v[128:129], v[74:75] op_sel_hi:[1,0,1]
	v_pk_fma_f32 v[120:121], v[120:121], v[128:129], v[72:73] op_sel_hi:[1,0,1]
	v_pk_fma_f32 v[118:119], v[118:119], v[128:129], v[70:71] op_sel_hi:[1,0,1]
	v_pk_fma_f32 v[116:117], v[116:117], v[128:129], v[68:69] op_sel_hi:[1,0,1]
	v_pk_fma_f32 v[114:115], v[114:115], v[128:129], v[66:67] op_sel_hi:[1,0,1]
	v_pk_fma_f32 v[112:113], v[112:113], v[128:129], v[64:65] op_sel_hi:[1,0,1]
	v_mul_f32_e32 v128, 0xbfb8aa3b, v124
	v_mul_f32_e32 v129, 0xbfb8aa3b, v125
	v_exp_f32_e32 v128, v128
	v_exp_f32_e32 v129, v129
	v_add_f32_e32 v128, 1.0, v128
	v_add_f32_e32 v129, 1.0, v129
	v_rcp_f32_e32 v128, v128
	v_rcp_f32_e32 v129, v129
	s_nop 0
	v_pk_mul_f32 v[124:125], v[124:125], v[128:129]
	s_nop 0
	v_pk_mul_f32 v[116:117], v[116:117], v[124:125]
	s_nop 0
	v_cvt_pk_bf16_f32 v116, v116, v117
	v_mul_f32_e32 v117, 0xbfb8aa3b, v126
	v_exp_f32_e32 v117, v117
	s_nop 0
	v_add_f32_e32 v117, 1.0, v117
	v_rcp_f32_e32 v124, v117
	v_mul_f32_e32 v117, 0xbfb8aa3b, v127
	v_exp_f32_e32 v117, v117
	s_nop 0
	v_add_f32_e32 v117, 1.0, v117
	v_rcp_f32_e32 v125, v117
	s_nop 0
	v_pk_mul_f32 v[124:125], v[126:127], v[124:125]
	s_nop 0
	v_pk_mul_f32 v[118:119], v[118:119], v[124:125]
	s_nop 0
	v_cvt_pk_bf16_f32 v117, v118, v119
	v_mul_f32_e32 v118, 0xbfb8aa3b, v120
	v_mul_f32_e32 v119, 0xbfb8aa3b, v121
	v_exp_f32_e32 v118, v118
	v_exp_f32_e32 v119, v119
	v_add_f32_e32 v118, 1.0, v118
	v_add_f32_e32 v119, 1.0, v119
; __device__ __forceinline__ float silu_f(float g) { return g * __builtin_amdgcn_rcpf(1.0f + __builtin_amdgcn_exp2f(-1.4426950408889634f * g)); }
;     __device__ __forceinline__ void operator()(const f32x4 (&acc)[2][2][4][2], const Unit& u, int wr, int wc, int fr, int fq) const {
;     ...
;             for (int m = 0; m < 4; ++m) {
;                 const float rs = __builtin_amdgcn_rsqf(rsv[ai][m] * (1.0f / 1024.0f) + 1e-6f);
;                 const f32x4 g0 = acc[ai][0][m][0] * rs + sv[0][0], g1 = acc[ai][0][m][1] * rs + sv[0][1], u0 = acc[ai][1][m][0] * rs + sv[1][0], u1 = acc[ai][1][m][1] * rs + sv[1][1];
;                 u32x4 w;
;                 w.x = cvt_pk_bf16(silu_f(g0[0]) * u0[0], silu_f(g0[1]) * u0[1]); w.y = cvt_pk_bf16(silu_f(g0[2]) * u0[2], silu_f(g0[3]) * u0[3]);
;                 w.z = cvt_pk_bf16(silu_f(g1[0]) * u1[0], silu_f(g1[1]) * u1[1]); w.w = cvt_pk_bf16(silu_f(g1[2]) * u1[2], silu_f(g1[3]) * u1[3]);
;                 __builtin_nontemporal_store(w, (u32x4*)(O + (size_t)(row0 + ai * HALF + m * 16) * ldc + col0));
	v_rcp_f32_e32 v118, v118
	v_rcp_f32_e32 v119, v119
	s_nop 0
	v_pk_mul_f32 v[118:119], v[120:121], v[118:119]
	s_nop 0
	v_pk_mul_f32 v[112:113], v[112:113], v[118:119]
	s_nop 0
	v_cvt_pk_bf16_f32 v118, v112, v113
	v_mul_f32_e32 v112, 0xbfb8aa3b, v122
	v_mul_f32_e32 v113, 0xbfb8aa3b, v123
	v_exp_f32_e32 v112, v112
	v_exp_f32_e32 v113, v113
	v_add_f32_e32 v112, 1.0, v112
	v_add_f32_e32 v113, 1.0, v113
	v_rcp_f32_e32 v112, v112
	v_rcp_f32_e32 v113, v113
	s_nop 0
	v_pk_mul_f32 v[112:113], v[122:123], v[112:113]
	s_nop 0
	v_pk_mul_f32 v[112:113], v[114:115], v[112:113]
	s_nop 0
	v_cvt_pk_bf16_f32 v119, v112, v113
	v_mad_i64_i32 v[112:113], s[4:5], v190, s31, v[132:133]
	v_lshl_add_u64 v[112:113], v[112:113], 0, v[134:135]
	global_store_dwordx4 v[112:113], v[116:119], off nt
	v_fmamk_f32 v112, v189, 0x3a800000, v222
	v_rsq_f32_e32 v112, v112
	s_nop 0
	v_pk_fma_f32 v[108:109], v[108:109], v[112:113], v[76:77] op_sel_hi:[1,0,1]
	v_pk_fma_f32 v[114:115], v[98:99], v[112:113], v[66:67] op_sel_hi:[1,0,1]
	v_pk_fma_f32 v[98:99], v[96:97], v[112:113], v[64:65] op_sel_hi:[1,0,1]
	v_mul_f32_e32 v96, 0xbfb8aa3b, v108
	v_mul_f32_e32 v97, 0xbfb8aa3b, v109
	v_exp_f32_e32 v96, v96
	v_exp_f32_e32 v97, v97
	v_pk_fma_f32 v[100:101], v[100:101], v[112:113], v[68:69] op_sel_hi:[1,0,1]
	v_pk_fma_f32 v[110:111], v[110:111], v[112:113], v[78:79] op_sel_hi:[1,0,1]
	v_add_f32_e32 v96, 1.0, v96
	v_add_f32_e32 v97, 1.0, v97
	v_rcp_f32_e32 v96, v96
	v_rcp_f32_e32 v97, v97
	v_pk_fma_f32 v[102:103], v[102:103], v[112:113], v[70:71] op_sel_hi:[1,0,1]
	v_pk_fma_f32 v[104:105], v[104:105], v[112:113], v[72:73] op_sel_hi:[1,0,1]
	v_pk_fma_f32 v[106:107], v[106:107], v[112:113], v[74:75] op_sel_hi:[1,0,1]
	v_pk_mul_f32 v[96:97], v[108:109], v[96:97]
	s_nop 0
	v_pk_mul_f32 v[96:97], v[100:101], v[96:97]
	s_nop 0
	v_cvt_pk_bf16_f32 v96, v96, v97
	v_mul_f32_e32 v97, 0xbfb8aa3b, v110
	v_exp_f32_e32 v97, v97
	s_nop 0
	v_add_f32_e32 v97, 1.0, v97
	v_rcp_f32_e32 v100, v97
	v_mul_f32_e32 v97, 0xbfb8aa3b, v111
	v_exp_f32_e32 v97, v97
	s_nop 0
	v_add_f32_e32 v97, 1.0, v97
	v_rcp_f32_e32 v101, v97
	s_nop 0
	v_pk_mul_f32 v[100:101], v[110:111], v[100:101]
	s_nop 0
	v_pk_mul_f32 v[100:101], v[102:103], v[100:101]
	s_nop 0
	v_cvt_pk_bf16_f32 v97, v100, v101
	v_mul_f32_e32 v100, 0xbfb8aa3b, v104
	v_mul_f32_e32 v101, 0xbfb8aa3b, v105
	v_exp_f32_e32 v100, v100
	v_exp_f32_e32 v101, v101
	v_add_f32_e32 v100, 1.0, v100
	v_add_f32_e32 v101, 1.0, v101
	v_rcp_f32_e32 v100, v100
	v_rcp_f32_e32 v101, v101
	s_nop 0
	v_pk_mul_f32 v[100:101], v[104:105], v[100:101]
	s_nop 0
	v_pk_mul_f32 v[98:99], v[98:99], v[100:101]
	s_nop 0
	v_cvt_pk_bf16_f32 v98, v98, v99
	v_mul_f32_e32 v99, 0xbfb8aa3b, v106
	v_exp_f32_e32 v99, v99
	s_nop 0
	v_add_f32_e32 v99, 1.0, v99
	v_rcp_f32_e32 v100, v99
	v_mul_f32_e32 v99, 0xbfb8aa3b, v107
	v_exp_f32_e32 v99, v99
	s_nop 0
	v_add_f32_e32 v99, 1.0, v99
	v_rcp_f32_e32 v101, v99
	s_nop 0
	v_pk_mul_f32 v[100:101], v[106:107], v[100:101]
	s_nop 0
	v_pk_mul_f32 v[100:101], v[114:115], v[100:101]
	s_nop 0
	v_cvt_pk_bf16_f32 v99, v100, v101
	v_mad_i64_i32 v[100:101], s[4:5], v188, s31, v[132:133]
	v_lshl_add_u64 v[100:101], v[100:101], 0, v[134:135]
	global_store_dwordx4 v[100:101], v[96:99], off nt
	s_nop 1
	v_fmamk_f32 v96, v187, 0x3a800000, v222
	v_rsq_f32_e32 v96, v96
	s_nop 0
	v_pk_fma_f32 v[92:93], v[92:93], v[96:97], v[76:77] op_sel_hi:[1,0,1]
	v_pk_fma_f32 v[98:99], v[82:83], v[96:97], v[66:67] op_sel_hi:[1,0,1]
	v_pk_fma_f32 v[82:83], v[80:81], v[96:97], v[64:65] op_sel_hi:[1,0,1]
	v_mul_f32_e32 v80, 0xbfb8aa3b, v92
	v_mul_f32_e32 v81, 0xbfb8aa3b, v93
	v_exp_f32_e32 v80, v80
	v_exp_f32_e32 v81, v81
	v_pk_fma_f32 v[84:85], v[84:85], v[96:97], v[68:69] op_sel_hi:[1,0,1]
	v_pk_fma_f32 v[94:95], v[94:95], v[96:97], v[78:79] op_sel_hi:[1,0,1]
	v_add_f32_e32 v80, 1.0, v80
	v_add_f32_e32 v81, 1.0, v81
	v_rcp_f32_e32 v80, v80
	v_rcp_f32_e32 v81, v81
	v_pk_fma_f32 v[86:87], v[86:87], v[96:97], v[70:71] op_sel_hi:[1,0,1]
	v_pk_fma_f32 v[88:89], v[88:89], v[96:97], v[72:73] op_sel_hi:[1,0,1]
	v_pk_fma_f32 v[90:91], v[90:91], v[96:97], v[74:75] op_sel_hi:[1,0,1]
	v_pk_mul_f32 v[80:81], v[92:93], v[80:81]
	s_nop 0
	v_pk_mul_f32 v[80:81], v[84:85], v[80:81]
	s_nop 0
	v_cvt_pk_bf16_f32 v80, v80, v81
	v_mul_f32_e32 v81, 0xbfb8aa3b, v94
	v_exp_f32_e32 v81, v81
	s_nop 0
	v_add_f32_e32 v81, 1.0, v81
	v_rcp_f32_e32 v84, v81
	v_mul_f32_e32 v81, 0xbfb8aa3b, v95
	v_exp_f32_e32 v81, v81
	s_nop 0
	v_add_f32_e32 v81, 1.0, v81
	v_rcp_f32_e32 v85, v81
	s_nop 0
	v_pk_mul_f32 v[84:85], v[94:95], v[84:85]
	s_nop 0
	v_pk_mul_f32 v[84:85], v[86:87], v[84:85]
	s_nop 0
	v_cvt_pk_bf16_f32 v81, v84, v85
	v_mul_f32_e32 v84, 0xbfb8aa3b, v88
	v_mul_f32_e32 v85, 0xbfb8aa3b, v89
	v_exp_f32_e32 v84, v84
	v_exp_f32_e32 v85, v85
	v_add_f32_e32 v84, 1.0, v84
	v_add_f32_e32 v85, 1.0, v85
	v_rcp_f32_e32 v84, v84
	v_rcp_f32_e32 v85, v85
	s_nop 0
	v_pk_mul_f32 v[84:85], v[88:89], v[84:85]
	s_nop 0
	v_pk_mul_f32 v[82:83], v[82:83], v[84:85]
	s_nop 0
	v_cvt_pk_bf16_f32 v82, v82, v83
	v_mul_f32_e32 v83, 0xbfb8aa3b, v90
	v_exp_f32_e32 v83, v83
	s_nop 0
	v_add_f32_e32 v83, 1.0, v83
	v_rcp_f32_e32 v84, v83
	v_mul_f32_e32 v83, 0xbfb8aa3b, v91
	v_exp_f32_e32 v83, v83
	s_nop 0
	v_add_f32_e32 v83, 1.0, v83
	v_rcp_f32_e32 v85, v83
	s_nop 0
	v_pk_mul_f32 v[84:85], v[90:91], v[84:85]
	s_nop 0
	v_pk_mul_f32 v[84:85], v[98:99], v[84:85]
	s_nop 0
	v_cvt_pk_bf16_f32 v83, v84, v85
	v_mad_i64_i32 v[84:85], s[4:5], v186, s31, v[132:133]
	v_lshl_add_u64 v[84:85], v[84:85], 0, v[134:135]
	global_store_dwordx4 v[84:85], v[80:83], off nt
	s_nop 1
	v_fmamk_f32 v80, v185, 0x3a800000, v222
	v_rsq_f32_e32 v80, v80
	s_nop 0
; __device__ __forceinline__ float silu_f(float g) { return g * __builtin_amdgcn_rcpf(1.0f + __builtin_amdgcn_exp2f(-1.4426950408889634f * g)); }
;     __device__ __forceinline__ void operator()(const f32x4 (&acc)[2][2][4][2], const Unit& u, int wr, int wc, int fr, int fq) const {
;     ...
;             for (int m = 0; m < 4; ++m) {
;                 const float rs = __builtin_amdgcn_rsqf(rsv[ai][m] * (1.0f / 1024.0f) + 1e-6f);
;                 const f32x4 g0 = acc[ai][0][m][0] * rs + sv[0][0], g1 = acc[ai][0][m][1] * rs + sv[0][1], u0 = acc[ai][1][m][0] * rs + sv[1][0], u1 = acc[ai][1][m][1] * rs + sv[1][1];
;                 u32x4 w;
;                 w.x = cvt_pk_bf16(silu_f(g0[0]) * u0[0], silu_f(g0[1]) * u0[1]); w.y = cvt_pk_bf16(silu_f(g0[2]) * u0[2], silu_f(g0[3]) * u0[3]);
;                 w.z = cvt_pk_bf16(silu_f(g1[0]) * u1[0], silu_f(g1[1]) * u1[1]); w.w = cvt_pk_bf16(silu_f(g1[2]) * u1[2], silu_f(g1[3]) * u1[3]);
;                 __builtin_nontemporal_store(w, (u32x4*)(O + (size_t)(row0 + ai * HALF + m * 16) * ldc + col0));
	v_pk_fma_f32 v[60:61], v[60:61], v[80:81], v[76:77] op_sel_hi:[1,0,1]
	v_pk_fma_f32 v[82:83], v[50:51], v[80:81], v[66:67] op_sel_hi:[1,0,1]
	v_pk_fma_f32 v[50:51], v[48:49], v[80:81], v[64:65] op_sel_hi:[1,0,1]
	v_mul_f32_e32 v48, 0xbfb8aa3b, v60
	v_mul_f32_e32 v49, 0xbfb8aa3b, v61
	v_exp_f32_e32 v48, v48
	v_exp_f32_e32 v49, v49
	v_pk_fma_f32 v[52:53], v[52:53], v[80:81], v[68:69] op_sel_hi:[1,0,1]
	v_pk_fma_f32 v[62:63], v[62:63], v[80:81], v[78:79] op_sel_hi:[1,0,1]
	v_add_f32_e32 v48, 1.0, v48
	v_add_f32_e32 v49, 1.0, v49
	v_rcp_f32_e32 v48, v48
	v_rcp_f32_e32 v49, v49
	v_pk_fma_f32 v[54:55], v[54:55], v[80:81], v[70:71] op_sel_hi:[1,0,1]
	v_pk_fma_f32 v[56:57], v[56:57], v[80:81], v[72:73] op_sel_hi:[1,0,1]
	v_pk_fma_f32 v[58:59], v[58:59], v[80:81], v[74:75] op_sel_hi:[1,0,1]
	v_pk_mul_f32 v[48:49], v[60:61], v[48:49]
	s_nop 0
	v_pk_mul_f32 v[48:49], v[52:53], v[48:49]
	s_nop 0
	v_cvt_pk_bf16_f32 v48, v48, v49
	v_mul_f32_e32 v49, 0xbfb8aa3b, v62
	v_exp_f32_e32 v49, v49
	s_nop 0
	v_add_f32_e32 v49, 1.0, v49
	v_rcp_f32_e32 v52, v49
	v_mul_f32_e32 v49, 0xbfb8aa3b, v63
	v_exp_f32_e32 v49, v49
	s_nop 0
	v_add_f32_e32 v49, 1.0, v49
	v_rcp_f32_e32 v53, v49
	s_nop 0
	v_pk_mul_f32 v[52:53], v[62:63], v[52:53]
	s_nop 0
	v_pk_mul_f32 v[52:53], v[54:55], v[52:53]
	s_nop 0
	v_cvt_pk_bf16_f32 v49, v52, v53
	v_mul_f32_e32 v52, 0xbfb8aa3b, v56
	v_mul_f32_e32 v53, 0xbfb8aa3b, v57
	v_exp_f32_e32 v52, v52
	v_exp_f32_e32 v53, v53
	v_add_f32_e32 v52, 1.0, v52
	v_add_f32_e32 v53, 1.0, v53
	v_rcp_f32_e32 v52, v52
	v_rcp_f32_e32 v53, v53
	s_nop 0
	v_pk_mul_f32 v[52:53], v[56:57], v[52:53]
	s_nop 0
	v_pk_mul_f32 v[50:51], v[50:51], v[52:53]
	s_nop 0
	v_cvt_pk_bf16_f32 v50, v50, v51
	v_mul_f32_e32 v51, 0xbfb8aa3b, v58
	v_exp_f32_e32 v51, v51
	s_nop 0
	v_add_f32_e32 v51, 1.0, v51
	v_rcp_f32_e32 v52, v51
	v_mul_f32_e32 v51, 0xbfb8aa3b, v59
	v_exp_f32_e32 v51, v51
	s_nop 0
	v_add_f32_e32 v51, 1.0, v51
	v_rcp_f32_e32 v53, v51
	s_nop 0
	v_pk_mul_f32 v[52:53], v[58:59], v[52:53]
	s_nop 0
	v_pk_mul_f32 v[52:53], v[82:83], v[52:53]
	s_nop 0
	v_cvt_pk_bf16_f32 v51, v52, v53
	v_mad_i64_i32 v[52:53], s[4:5], v183, s31, v[132:133]
	v_lshl_add_u64 v[52:53], v[52:53], 0, v[134:135]
	global_store_dwordx4 v[52:53], v[48:51], off nt
	s_nop 1
	v_fmamk_f32 v48, v167, 0x3a800000, v222
	v_rsq_f32_e32 v48, v48
	s_nop 0
	v_pk_fma_f32 v[44:45], v[44:45], v[48:49], v[76:77] op_sel_hi:[1,0,1]
	v_pk_fma_f32 v[50:51], v[34:35], v[48:49], v[66:67] op_sel_hi:[1,0,1]
	v_pk_fma_f32 v[34:35], v[32:33], v[48:49], v[64:65] op_sel_hi:[1,0,1]
	v_mul_f32_e32 v32, 0xbfb8aa3b, v44
	v_mul_f32_e32 v33, 0xbfb8aa3b, v45
	v_exp_f32_e32 v32, v32
	v_exp_f32_e32 v33, v33
	v_pk_fma_f32 v[36:37], v[36:37], v[48:49], v[68:69] op_sel_hi:[1,0,1]
	v_pk_fma_f32 v[46:47], v[46:47], v[48:49], v[78:79] op_sel_hi:[1,0,1]
	v_add_f32_e32 v32, 1.0, v32
	v_add_f32_e32 v33, 1.0, v33
	v_rcp_f32_e32 v32, v32
	v_rcp_f32_e32 v33, v33
	v_pk_fma_f32 v[38:39], v[38:39], v[48:49], v[70:71] op_sel_hi:[1,0,1]
	v_pk_fma_f32 v[40:41], v[40:41], v[48:49], v[72:73] op_sel_hi:[1,0,1]
	v_pk_fma_f32 v[42:43], v[42:43], v[48:49], v[74:75] op_sel_hi:[1,0,1]
	v_pk_mul_f32 v[32:33], v[44:45], v[32:33]
	s_nop 0
	v_pk_mul_f32 v[32:33], v[36:37], v[32:33]
	s_nop 0
	v_cvt_pk_bf16_f32 v32, v32, v33
	v_mul_f32_e32 v33, 0xbfb8aa3b, v46
	v_exp_f32_e32 v33, v33
	s_nop 0
	v_add_f32_e32 v33, 1.0, v33
	v_rcp_f32_e32 v36, v33
	v_mul_f32_e32 v33, 0xbfb8aa3b, v47
	v_exp_f32_e32 v33, v33
	s_nop 0
	v_add_f32_e32 v33, 1.0, v33
	v_rcp_f32_e32 v37, v33
	s_nop 0
	v_pk_mul_f32 v[36:37], v[46:47], v[36:37]
	s_nop 0
	v_pk_mul_f32 v[36:37], v[38:39], v[36:37]
	s_nop 0
	v_cvt_pk_bf16_f32 v33, v36, v37
	v_mul_f32_e32 v36, 0xbfb8aa3b, v40
	v_mul_f32_e32 v37, 0xbfb8aa3b, v41
	v_exp_f32_e32 v36, v36
	v_exp_f32_e32 v37, v37
	v_add_f32_e32 v36, 1.0, v36
	v_add_f32_e32 v37, 1.0, v37
	v_rcp_f32_e32 v36, v36
	v_rcp_f32_e32 v37, v37
	s_nop 0
	v_pk_mul_f32 v[36:37], v[40:41], v[36:37]
	s_nop 0
	v_pk_mul_f32 v[34:35], v[34:35], v[36:37]
	s_nop 0
	v_cvt_pk_bf16_f32 v34, v34, v35
	v_mul_f32_e32 v35, 0xbfb8aa3b, v42
	v_exp_f32_e32 v35, v35
	s_nop 0
	v_add_f32_e32 v35, 1.0, v35
	v_rcp_f32_e32 v36, v35
	v_mul_f32_e32 v35, 0xbfb8aa3b, v43
	v_exp_f32_e32 v35, v35
	s_nop 0
	v_add_f32_e32 v35, 1.0, v35
	v_rcp_f32_e32 v37, v35
	s_nop 0
	v_pk_mul_f32 v[36:37], v[42:43], v[36:37]
	s_nop 0
	v_pk_mul_f32 v[36:37], v[50:51], v[36:37]
	s_nop 0
	v_cvt_pk_bf16_f32 v35, v36, v37
	v_mad_i64_i32 v[36:37], s[4:5], v166, s31, v[132:133]
	v_lshl_add_u64 v[36:37], v[36:37], 0, v[134:135]
	global_store_dwordx4 v[36:37], v[32:35], off nt
	s_nop 1
	v_fmamk_f32 v32, v165, 0x3a800000, v222
; __device__ __forceinline__ float silu_f(float g) { return g * __builtin_amdgcn_rcpf(1.0f + __builtin_amdgcn_exp2f(-1.4426950408889634f * g)); }
;     __device__ __forceinline__ void operator()(const f32x4 (&acc)[2][2][4][2], const Unit& u, int wr, int wc, int fr, int fq) const {
;     ...
;             for (int m = 0; m < 4; ++m) {
;                 const float rs = __builtin_amdgcn_rsqf(rsv[ai][m] * (1.0f / 1024.0f) + 1e-6f);
;                 const f32x4 g0 = acc[ai][0][m][0] * rs + sv[0][0], g1 = acc[ai][0][m][1] * rs + sv[0][1], u0 = acc[ai][1][m][0] * rs + sv[1][0], u1 = acc[ai][1][m][1] * rs + sv[1][1];
;                 u32x4 w;
;                 w.x = cvt_pk_bf16(silu_f(g0[0]) * u0[0], silu_f(g0[1]) * u0[1]); w.y = cvt_pk_bf16(silu_f(g0[2]) * u0[2], silu_f(g0[3]) * u0[3]);
;                 w.z = cvt_pk_bf16(silu_f(g1[0]) * u1[0], silu_f(g1[1]) * u1[1]); w.w = cvt_pk_bf16(silu_f(g1[2]) * u1[2], silu_f(g1[3]) * u1[3]);
;                 __builtin_nontemporal_store(w, (u32x4*)(O + (size_t)(row0 + ai * HALF + m * 16) * ldc + col0));
; template <class Epi, class Sched, bool ALIGN_EPI = false, bool SP2 = false>
; __device__ __forceinline__ void gemm_phase(PG8_LAS unsigned char* lds, const int tid, const Gemm g, const Sched& S, const Epi& E) {
;     ...
;         if constexpr (!Epi::AFTER_DRAIN) { E(acc, cur, wr, wc, fr, fq); S.done(cur); }
;         if (!has_next) break;
	v_rsq_f32_e32 v32, v32
	s_nop 0
	v_pk_fma_f32 v[28:29], v[28:29], v[32:33], v[76:77] op_sel_hi:[1,0,1]
	v_pk_fma_f32 v[34:35], v[18:19], v[32:33], v[66:67] op_sel_hi:[1,0,1]
	v_pk_fma_f32 v[18:19], v[16:17], v[32:33], v[64:65] op_sel_hi:[1,0,1]
	v_mul_f32_e32 v16, 0xbfb8aa3b, v28
	v_mul_f32_e32 v17, 0xbfb8aa3b, v29
	v_exp_f32_e32 v16, v16
	v_exp_f32_e32 v17, v17
	v_pk_fma_f32 v[20:21], v[20:21], v[32:33], v[68:69] op_sel_hi:[1,0,1]
	v_pk_fma_f32 v[30:31], v[30:31], v[32:33], v[78:79] op_sel_hi:[1,0,1]
	v_add_f32_e32 v16, 1.0, v16
	v_add_f32_e32 v17, 1.0, v17
	v_rcp_f32_e32 v16, v16
	v_rcp_f32_e32 v17, v17
	v_pk_fma_f32 v[22:23], v[22:23], v[32:33], v[70:71] op_sel_hi:[1,0,1]
	v_pk_fma_f32 v[24:25], v[24:25], v[32:33], v[72:73] op_sel_hi:[1,0,1]
	v_pk_fma_f32 v[26:27], v[26:27], v[32:33], v[74:75] op_sel_hi:[1,0,1]
	v_pk_mul_f32 v[16:17], v[28:29], v[16:17]
	s_nop 0
	v_pk_mul_f32 v[16:17], v[20:21], v[16:17]
	s_nop 0
	v_cvt_pk_bf16_f32 v16, v16, v17
	v_mul_f32_e32 v17, 0xbfb8aa3b, v30
	v_exp_f32_e32 v17, v17
	s_nop 0
	v_add_f32_e32 v17, 1.0, v17
	v_rcp_f32_e32 v20, v17
	v_mul_f32_e32 v17, 0xbfb8aa3b, v31
	v_exp_f32_e32 v17, v17
	s_nop 0
	v_add_f32_e32 v17, 1.0, v17
	v_rcp_f32_e32 v21, v17
	s_nop 0
	v_pk_mul_f32 v[20:21], v[30:31], v[20:21]
	s_nop 0
	v_pk_mul_f32 v[20:21], v[22:23], v[20:21]
	s_nop 0
	v_cvt_pk_bf16_f32 v17, v20, v21
	v_mul_f32_e32 v20, 0xbfb8aa3b, v24
	v_mul_f32_e32 v21, 0xbfb8aa3b, v25
	v_exp_f32_e32 v20, v20
	v_exp_f32_e32 v21, v21
	v_add_f32_e32 v20, 1.0, v20
	v_add_f32_e32 v21, 1.0, v21
	v_rcp_f32_e32 v20, v20
	v_rcp_f32_e32 v21, v21
	s_nop 0
	v_pk_mul_f32 v[20:21], v[24:25], v[20:21]
	s_nop 0
	v_pk_mul_f32 v[18:19], v[18:19], v[20:21]
	s_nop 0
	v_cvt_pk_bf16_f32 v18, v18, v19
	v_mul_f32_e32 v19, 0xbfb8aa3b, v26
	v_exp_f32_e32 v19, v19
	s_nop 0
	v_add_f32_e32 v19, 1.0, v19
	v_rcp_f32_e32 v20, v19
	v_mul_f32_e32 v19, 0xbfb8aa3b, v27
	v_exp_f32_e32 v19, v19
	s_nop 0
	v_add_f32_e32 v19, 1.0, v19
	v_rcp_f32_e32 v21, v19
	s_nop 0
	v_pk_mul_f32 v[20:21], v[26:27], v[20:21]
	s_nop 0
	v_pk_mul_f32 v[20:21], v[34:35], v[20:21]
	s_nop 0
	v_cvt_pk_bf16_f32 v19, v20, v21
	v_mad_i64_i32 v[20:21], s[4:5], v164, s31, v[132:133]
	v_lshl_add_u64 v[20:21], v[20:21], 0, v[134:135]
	global_store_dwordx4 v[20:21], v[16:19], off nt
	s_nop 1
	v_fmamk_f32 v16, v163, 0x3a800000, v222
	v_rsq_f32_e32 v16, v16
	s_nop 0
	v_pk_fma_f32 v[12:13], v[12:13], v[16:17], v[76:77] op_sel_hi:[1,0,1]
	v_pk_fma_f32 v[18:19], v[2:3], v[16:17], v[66:67] op_sel_hi:[1,0,1]
	v_pk_fma_f32 v[2:3], v[0:1], v[16:17], v[64:65] op_sel_hi:[1,0,1]
	v_mul_f32_e32 v0, 0xbfb8aa3b, v12
	v_mul_f32_e32 v1, 0xbfb8aa3b, v13
	v_exp_f32_e32 v0, v0
	v_exp_f32_e32 v1, v1
	v_pk_fma_f32 v[4:5], v[4:5], v[16:17], v[68:69] op_sel_hi:[1,0,1]
	v_pk_fma_f32 v[14:15], v[14:15], v[16:17], v[78:79] op_sel_hi:[1,0,1]
	v_add_f32_e32 v0, 1.0, v0
	v_add_f32_e32 v1, 1.0, v1
	v_rcp_f32_e32 v0, v0
	v_rcp_f32_e32 v1, v1
	v_pk_fma_f32 v[6:7], v[6:7], v[16:17], v[70:71] op_sel_hi:[1,0,1]
	v_pk_fma_f32 v[8:9], v[8:9], v[16:17], v[72:73] op_sel_hi:[1,0,1]
	v_pk_fma_f32 v[10:11], v[10:11], v[16:17], v[74:75] op_sel_hi:[1,0,1]
	v_pk_mul_f32 v[0:1], v[12:13], v[0:1]
	s_nop 0
	v_pk_mul_f32 v[0:1], v[4:5], v[0:1]
	s_nop 0
	v_cvt_pk_bf16_f32 v0, v0, v1
	v_mul_f32_e32 v1, 0xbfb8aa3b, v14
	v_exp_f32_e32 v1, v1
	s_nop 0
	v_add_f32_e32 v1, 1.0, v1
	v_rcp_f32_e32 v4, v1
	v_mul_f32_e32 v1, 0xbfb8aa3b, v15
	v_exp_f32_e32 v1, v1
	s_nop 0
	v_add_f32_e32 v1, 1.0, v1
	v_rcp_f32_e32 v5, v1
	s_nop 0
	v_pk_mul_f32 v[4:5], v[14:15], v[4:5]
	s_nop 0
	v_pk_mul_f32 v[4:5], v[6:7], v[4:5]
	s_nop 0
	v_cvt_pk_bf16_f32 v1, v4, v5
	v_mul_f32_e32 v4, 0xbfb8aa3b, v8
	v_mul_f32_e32 v5, 0xbfb8aa3b, v9
	v_exp_f32_e32 v4, v4
	v_exp_f32_e32 v5, v5
	v_add_f32_e32 v4, 1.0, v4
	v_add_f32_e32 v5, 1.0, v5
	v_rcp_f32_e32 v4, v4
	v_rcp_f32_e32 v5, v5
	s_nop 0
	v_pk_mul_f32 v[4:5], v[8:9], v[4:5]
	s_nop 0
	v_pk_mul_f32 v[2:3], v[2:3], v[4:5]
	s_nop 0
	v_cvt_pk_bf16_f32 v2, v2, v3
	v_mul_f32_e32 v3, 0xbfb8aa3b, v10
	v_exp_f32_e32 v3, v3
	s_nop 0
	v_add_f32_e32 v3, 1.0, v3
	v_rcp_f32_e32 v4, v3
	v_mul_f32_e32 v3, 0xbfb8aa3b, v11
	v_exp_f32_e32 v3, v3
	s_nop 0
	v_add_f32_e32 v3, 1.0, v3
	v_rcp_f32_e32 v5, v3
	s_nop 0
	v_pk_mul_f32 v[4:5], v[10:11], v[4:5]
	s_nop 0
	v_pk_mul_f32 v[4:5], v[18:19], v[4:5]
	s_nop 0
	v_cvt_pk_bf16_f32 v3, v4, v5
	v_mad_i64_i32 v[4:5], s[4:5], v155, s31, v[132:133]
	v_lshl_add_u64 v[4:5], v[4:5], 0, v[134:135]
	s_mov_b64 s[4:5], -1
	global_store_dwordx4 v[4:5], v[0:3], off nt
	s_cbranch_vccnz .LBB0_420
	s_andn2_b64 vcc, exec, s[2:3]
	s_cbranch_vccnz .LBB0_419
	s_barrier
	s_branch .LBB0_419
